# combo9 + K-loop LDS-DMA rebalance, two pieces moved from the first K-tile's L2 segment to the head of the next L1 segment (2/4/4/6, wait vmcnt(6))
# speedup vs baseline: 1.0082x; 1.0002x over previous
.LBB0_324:
	s_add_i32 vcc_lo, s66, 2
	s_add_u32 s34, s8, 0xfff00080
	s_addc_u32 s35, s9, -1
	s_add_i32 s89, 0, 0x10000
	s_cmp_eq_u32 s59, s66
	s_cselect_b32 s95, s65, s35
	s_cselect_b32 s94, s64, s34
	v_add_u32_e32 v0, s89, v217
	s_cselect_b32 s67, s53, s80
	s_cselect_b32 s66, s52, s70
	s_add_i32 vcc_hi, 0, 0x14000
	ds_read_b128 v[132:135], v0
	ds_read_b128 v[136:139], v0 offset:1024
	ds_read_b128 v[140:143], v0 offset:2048
	ds_read_b128 v[144:147], v0 offset:3072
	v_add_u32_e32 v0, vcc_hi, v217
	ds_read_b128 v[148:151], v0
	ds_read_b128 v[152:155], v0 offset:1024
	ds_read_b128 v[156:159], v0 offset:2048
	ds_read_b128 v[160:163], v0 offset:3072
	v_add_u32_e32 v0, 0, v216
	s_add_i32 m0, s29, 0xc000
	ds_read_b128 v[164:167], v0
	ds_read_b128 v[168:171], v0 offset:1024
	ds_read_b128 v[172:175], v0 offset:2048
	ds_read_b128 v[176:179], v0 offset:3072
	ds_read_b128 v[180:183], v0 offset:4096
	ds_read_b128 v[184:187], v0 offset:5120
	ds_read_b128 v[188:191], v0 offset:6144
	ds_read_b128 v[250:253], v0 offset:7168
	global_load_lds_dwordx4 v204, s[8:9]
	s_add_i32 m0, s29, 0xe000
	s_nop 0
	global_load_lds_dwordx4 v206, s[8:9]
	s_waitcnt vmcnt(8) lgkmcnt(0)
	s_barrier
	v_mfma_f32_16x16x32_bf16 v[128:131], v[132:135], v[164:167], v[128:131]
	v_mfma_f32_16x16x32_bf16 v[112:115], v[140:143], v[164:167], v[112:115]
	v_mfma_f32_16x16x32_bf16 v[120:123], v[132:135], v[172:175], v[120:123]
	v_mfma_f32_16x16x32_bf16 v[96:99], v[140:143], v[172:175], v[96:99]
	v_mfma_f32_16x16x32_bf16 v[104:107], v[132:135], v[180:183], v[104:107]
	v_mfma_f32_16x16x32_bf16 v[88:91], v[140:143], v[180:183], v[88:91]
	v_mfma_f32_16x16x32_bf16 v[84:87], v[132:135], v[188:191], v[84:87]
	v_mfma_f32_16x16x32_bf16 v[72:75], v[140:143], v[188:191], v[72:75]
	v_mfma_f32_16x16x32_bf16 v[128:131], v[136:139], v[168:171], v[128:131]
	v_mfma_f32_16x16x32_bf16 v[112:115], v[144:147], v[168:171], v[112:115]
	v_mfma_f32_16x16x32_bf16 v[120:123], v[136:139], v[176:179], v[120:123]
	v_mfma_f32_16x16x32_bf16 v[96:99], v[144:147], v[176:179], v[96:99]
	v_mfma_f32_16x16x32_bf16 v[104:107], v[136:139], v[184:187], v[104:107]
	v_mfma_f32_16x16x32_bf16 v[88:91], v[144:147], v[184:187], v[88:91]
	v_mfma_f32_16x16x32_bf16 v[84:87], v[136:139], v[250:253], v[84:87]
	v_mfma_f32_16x16x32_bf16 v[72:75], v[144:147], v[250:253], v[72:75]
	v_mfma_f32_16x16x32_bf16 v[124:127], v[148:151], v[164:167], v[124:127]
	v_mfma_f32_16x16x32_bf16 v[108:111], v[156:159], v[164:167], v[108:111]
	v_mfma_f32_16x16x32_bf16 v[116:119], v[148:151], v[172:175], v[116:119]
	v_mfma_f32_16x16x32_bf16 v[92:95], v[156:159], v[172:175], v[92:95]
	v_mfma_f32_16x16x32_bf16 v[100:103], v[148:151], v[180:183], v[100:103]
	v_mfma_f32_16x16x32_bf16 v[80:83], v[156:159], v[180:183], v[80:83]
	v_mfma_f32_16x16x32_bf16 v[76:79], v[148:151], v[188:191], v[76:79]
	v_mfma_f32_16x16x32_bf16 v[68:71], v[156:159], v[188:191], v[68:71]
	v_mfma_f32_16x16x32_bf16 v[124:127], v[152:155], v[168:171], v[124:127]
	v_mfma_f32_16x16x32_bf16 v[108:111], v[160:163], v[168:171], v[108:111]
	v_mfma_f32_16x16x32_bf16 v[116:119], v[152:155], v[176:179], v[116:119]
	v_mfma_f32_16x16x32_bf16 v[92:95], v[160:163], v[176:179], v[92:95]
	v_mfma_f32_16x16x32_bf16 v[100:103], v[152:155], v[184:187], v[100:103]
	v_mfma_f32_16x16x32_bf16 v[80:83], v[160:163], v[184:187], v[80:83]
	v_mfma_f32_16x16x32_bf16 v[76:79], v[152:155], v[250:253], v[76:79]
	v_mfma_f32_16x16x32_bf16 v[68:71], v[160:163], v[250:253], v[68:71]
	s_barrier
	s_add_i32 s34, s89, s0
	s_mov_b32 m0, s34
	ds_read_b128 v[164:167], v0 offset:16384
	ds_read_b128 v[168:171], v0 offset:17408
	ds_read_b128 v[172:175], v0 offset:18432
	ds_read_b128 v[176:179], v0 offset:19456
	ds_read_b128 v[180:183], v0 offset:20480
	ds_read_b128 v[184:187], v0 offset:21504
	ds_read_b128 v[188:191], v0 offset:22528
	ds_read_b128 v[250:253], v0 offset:23552
	global_load_lds_dwordx4 v196, s[66:67]
	s_add_i32 m0, s34, 0x2000
	s_add_u32 s34, s66, 0x4000
	s_addc_u32 s35, s67, 0
	s_add_i32 s89, vcc_hi, s0
	global_load_lds_dwordx4 v200, s[66:67]
	s_mov_b32 m0, s89
	s_nop 0
	global_load_lds_dwordx4 v196, s[34:35]
	s_add_i32 m0, s89, 0x2000
	s_nop 0
	global_load_lds_dwordx4 v200, s[34:35]
	s_waitcnt vmcnt(6) lgkmcnt(0)
	s_barrier
	v_mfma_f32_16x16x32_bf16 v[64:67], v[132:135], v[164:167], v[64:67]
	v_mfma_f32_16x16x32_bf16 v[56:59], v[140:143], v[164:167], v[56:59]
	v_mfma_f32_16x16x32_bf16 v[48:51], v[132:135], v[172:175], v[48:51]
	v_mfma_f32_16x16x32_bf16 v[40:43], v[140:143], v[172:175], v[40:43]
	v_mfma_f32_16x16x32_bf16 v[30:33], v[132:135], v[180:183], v[30:33]
	v_mfma_f32_16x16x32_bf16 v[26:29], v[140:143], v[180:183], v[26:29]
	v_mfma_f32_16x16x32_bf16 v[14:17], v[132:135], v[188:191], v[14:17]
	v_mfma_f32_16x16x32_bf16 v[10:13], v[140:143], v[188:191], v[10:13]
	v_mfma_f32_16x16x32_bf16 v[64:67], v[136:139], v[168:171], v[64:67]
	v_mfma_f32_16x16x32_bf16 v[56:59], v[144:147], v[168:171], v[56:59]
	v_mfma_f32_16x16x32_bf16 v[48:51], v[136:139], v[176:179], v[48:51]
	v_mfma_f32_16x16x32_bf16 v[40:43], v[144:147], v[176:179], v[40:43]
	v_mfma_f32_16x16x32_bf16 v[30:33], v[136:139], v[184:187], v[30:33]
	v_mfma_f32_16x16x32_bf16 v[26:29], v[144:147], v[184:187], v[26:29]
	v_mfma_f32_16x16x32_bf16 v[14:17], v[136:139], v[250:253], v[14:17]
	v_mfma_f32_16x16x32_bf16 v[10:13], v[144:147], v[250:253], v[10:13]
	v_mfma_f32_16x16x32_bf16 v[60:63], v[148:151], v[164:167], v[60:63]
	v_mfma_f32_16x16x32_bf16 v[52:55], v[156:159], v[164:167], v[52:55]
	v_mfma_f32_16x16x32_bf16 v[44:47], v[148:151], v[172:175], v[44:47]
	v_mfma_f32_16x16x32_bf16 v[36:39], v[156:159], v[172:175], v[36:39]
	v_mfma_f32_16x16x32_bf16 v[22:25], v[148:151], v[180:183], v[22:25]
	v_mfma_f32_16x16x32_bf16 v[18:21], v[156:159], v[180:183], v[18:21]
	v_mfma_f32_16x16x32_bf16 v[6:9], v[148:151], v[188:191], v[6:9]
	v_mfma_f32_16x16x32_bf16 v[2:5], v[156:159], v[188:191], v[2:5]
	v_mfma_f32_16x16x32_bf16 v[60:63], v[152:155], v[168:171], v[60:63]
	v_mfma_f32_16x16x32_bf16 v[52:55], v[160:163], v[168:171], v[52:55]
	v_mfma_f32_16x16x32_bf16 v[44:47], v[152:155], v[176:179], v[44:47]
	v_mfma_f32_16x16x32_bf16 v[36:39], v[160:163], v[176:179], v[36:39]
	v_mfma_f32_16x16x32_bf16 v[22:25], v[152:155], v[184:187], v[22:25]
	v_mfma_f32_16x16x32_bf16 v[18:21], v[160:163], v[184:187], v[18:21]
	v_mfma_f32_16x16x32_bf16 v[6:9], v[152:155], v[250:253], v[6:9]
	v_mfma_f32_16x16x32_bf16 v[2:5], v[160:163], v[250:253], v[2:5]
	s_barrier
	s_mov_b32 m0, s29
	s_nop 0
	global_load_lds_dwordx4 v198, s[94:95]
	s_mov_b32 m0, s45
	s_nop 0
	global_load_lds_dwordx4 v202, s[94:95]
	s_add_i32 s89, 0, 0x18000
	s_add_i32 vcc_hi, 0, 0x1c000
	v_add_u32_e32 v144, s89, v217
	v_add_u32_e32 v160, vcc_hi, v217
	ds_read_b128 v[132:135], v144
	ds_read_b128 v[136:139], v144 offset:1024
	ds_read_b128 v[140:143], v144 offset:2048
	ds_read_b128 v[144:147], v144 offset:3072
	ds_read_b128 v[148:151], v160
	ds_read_b128 v[152:155], v160 offset:1024
	ds_read_b128 v[156:159], v160 offset:2048
	ds_read_b128 v[160:163], v160 offset:3072
	s_add_u32 s34, s94, 0x100000
	s_addc_u32 s35, s95, 0
	s_mov_b32 m0, s82
	ds_read_b128 v[164:167], v0 offset:32768
	ds_read_b128 v[168:171], v0 offset:33792
	ds_read_b128 v[172:175], v0 offset:34816
	ds_read_b128 v[176:179], v0 offset:35840
	ds_read_b128 v[180:183], v0 offset:36864
	ds_read_b128 v[184:187], v0 offset:37888
	ds_read_b128 v[188:191], v0 offset:38912
	ds_read_b128 v[250:253], v0 offset:39936
	global_load_lds_dwordx4 v198, s[34:35]
	s_mov_b32 m0, s90
	s_nop 0
	global_load_lds_dwordx4 v202, s[34:35]
	s_waitcnt vmcnt(8) lgkmcnt(0)
	s_barrier
	v_mfma_f32_16x16x32_bf16 v[128:131], v[132:135], v[164:167], v[128:131]
	v_mfma_f32_16x16x32_bf16 v[112:115], v[140:143], v[164:167], v[112:115]
	v_mfma_f32_16x16x32_bf16 v[120:123], v[132:135], v[172:175], v[120:123]
	v_mfma_f32_16x16x32_bf16 v[96:99], v[140:143], v[172:175], v[96:99]
	v_mfma_f32_16x16x32_bf16 v[104:107], v[132:135], v[180:183], v[104:107]
	v_mfma_f32_16x16x32_bf16 v[88:91], v[140:143], v[180:183], v[88:91]
	v_mfma_f32_16x16x32_bf16 v[84:87], v[132:135], v[188:191], v[84:87]
	v_mfma_f32_16x16x32_bf16 v[72:75], v[140:143], v[188:191], v[72:75]
	v_mfma_f32_16x16x32_bf16 v[128:131], v[136:139], v[168:171], v[128:131]
	v_mfma_f32_16x16x32_bf16 v[112:115], v[144:147], v[168:171], v[112:115]
	v_mfma_f32_16x16x32_bf16 v[120:123], v[136:139], v[176:179], v[120:123]
	v_mfma_f32_16x16x32_bf16 v[96:99], v[144:147], v[176:179], v[96:99]
	v_mfma_f32_16x16x32_bf16 v[104:107], v[136:139], v[184:187], v[104:107]
	v_mfma_f32_16x16x32_bf16 v[88:91], v[144:147], v[184:187], v[88:91]
	v_mfma_f32_16x16x32_bf16 v[84:87], v[136:139], v[250:253], v[84:87]
	v_mfma_f32_16x16x32_bf16 v[72:75], v[144:147], v[250:253], v[72:75]
	v_mfma_f32_16x16x32_bf16 v[124:127], v[148:151], v[164:167], v[124:127]
	v_mfma_f32_16x16x32_bf16 v[108:111], v[156:159], v[164:167], v[108:111]
	v_mfma_f32_16x16x32_bf16 v[116:119], v[148:151], v[172:175], v[116:119]
	v_mfma_f32_16x16x32_bf16 v[92:95], v[156:159], v[172:175], v[92:95]
	v_mfma_f32_16x16x32_bf16 v[100:103], v[148:151], v[180:183], v[100:103]
	v_mfma_f32_16x16x32_bf16 v[80:83], v[156:159], v[180:183], v[80:83]
	v_mfma_f32_16x16x32_bf16 v[76:79], v[148:151], v[188:191], v[76:79]
	v_mfma_f32_16x16x32_bf16 v[68:71], v[156:159], v[188:191], v[68:71]
	v_mfma_f32_16x16x32_bf16 v[124:127], v[152:155], v[168:171], v[124:127]
	v_mfma_f32_16x16x32_bf16 v[108:111], v[160:163], v[168:171], v[108:111]
	v_mfma_f32_16x16x32_bf16 v[116:119], v[152:155], v[176:179], v[116:119]
	v_mfma_f32_16x16x32_bf16 v[92:95], v[160:163], v[176:179], v[92:95]
	v_mfma_f32_16x16x32_bf16 v[100:103], v[152:155], v[184:187], v[100:103]
	v_mfma_f32_16x16x32_bf16 v[80:83], v[160:163], v[184:187], v[80:83]
	v_mfma_f32_16x16x32_bf16 v[76:79], v[152:155], v[250:253], v[76:79]
	v_mfma_f32_16x16x32_bf16 v[68:71], v[160:163], v[250:253], v[68:71]
	s_barrier
	s_add_u32 s34, s66, 0x8000
	s_addc_u32 s35, s67, 0
	s_add_i32 s89, s89, s0
	s_mov_b32 m0, s89
	ds_read_b128 v[164:167], v0 offset:49152
	ds_read_b128 v[168:171], v0 offset:50176
	ds_read_b128 v[172:175], v0 offset:51200
	ds_read_b128 v[176:179], v0 offset:52224
	ds_read_b128 v[180:183], v0 offset:53248
	ds_read_b128 v[184:187], v0 offset:54272
	ds_read_b128 v[188:191], v0 offset:55296
	ds_read_b128 v[250:253], v0 offset:56320
	global_load_lds_dwordx4 v196, s[34:35]
	s_add_i32 m0, s89, 0x2000
	v_lshl_add_u64 v[210:211], s[34:35], 0, v[200:201]
	s_add_u32 s34, s66, 0xc000
	s_addc_u32 s35, s67, 0
	s_add_i32 s66, vcc_hi, s0
	global_load_lds_dwordx4 v[210:211], off
	s_mov_b32 m0, s66
	s_nop 0
	global_load_lds_dwordx4 v196, s[34:35]
	s_add_i32 m0, s66, 0x2000
	s_nop 0
	global_load_lds_dwordx4 v200, s[34:35]
	s_mov_b32 m0, s91
	s_nop 0
	s_add_u32 s100, s94, s92
	s_addc_u32 s101, s95, s93
	global_load_lds_dwordx4 v198, s[100:101]
	s_mov_b32 m0, s30
	s_nop 0
	s_add_u32 s100, s94, s92
	s_addc_u32 s101, s95, s93
	global_load_lds_dwordx4 v202, s[100:101]
	s_waitcnt vmcnt(8) lgkmcnt(0)
	s_barrier
	v_mfma_f32_16x16x32_bf16 v[64:67], v[132:135], v[164:167], v[64:67]
	v_mfma_f32_16x16x32_bf16 v[56:59], v[140:143], v[164:167], v[56:59]
	v_mfma_f32_16x16x32_bf16 v[48:51], v[132:135], v[172:175], v[48:51]
	v_mfma_f32_16x16x32_bf16 v[40:43], v[140:143], v[172:175], v[40:43]
	v_mfma_f32_16x16x32_bf16 v[30:33], v[132:135], v[180:183], v[30:33]
	v_mfma_f32_16x16x32_bf16 v[26:29], v[140:143], v[180:183], v[26:29]
	v_mfma_f32_16x16x32_bf16 v[14:17], v[132:135], v[188:191], v[14:17]
	v_mfma_f32_16x16x32_bf16 v[10:13], v[140:143], v[188:191], v[10:13]
	v_mfma_f32_16x16x32_bf16 v[64:67], v[136:139], v[168:171], v[64:67]
	v_mfma_f32_16x16x32_bf16 v[56:59], v[144:147], v[168:171], v[56:59]
	v_mfma_f32_16x16x32_bf16 v[48:51], v[136:139], v[176:179], v[48:51]
	v_mfma_f32_16x16x32_bf16 v[40:43], v[144:147], v[176:179], v[40:43]
	v_mfma_f32_16x16x32_bf16 v[30:33], v[136:139], v[184:187], v[30:33]
	v_mfma_f32_16x16x32_bf16 v[26:29], v[144:147], v[184:187], v[26:29]
	v_mfma_f32_16x16x32_bf16 v[14:17], v[136:139], v[250:253], v[14:17]
	v_mfma_f32_16x16x32_bf16 v[10:13], v[144:147], v[250:253], v[10:13]
	v_mfma_f32_16x16x32_bf16 v[60:63], v[148:151], v[164:167], v[60:63]
	v_mfma_f32_16x16x32_bf16 v[52:55], v[156:159], v[164:167], v[52:55]
	v_mfma_f32_16x16x32_bf16 v[44:47], v[148:151], v[172:175], v[44:47]
	v_mfma_f32_16x16x32_bf16 v[36:39], v[156:159], v[172:175], v[36:39]
	v_mfma_f32_16x16x32_bf16 v[22:25], v[148:151], v[180:183], v[22:25]
	v_mfma_f32_16x16x32_bf16 v[18:21], v[156:159], v[180:183], v[18:21]
	v_mfma_f32_16x16x32_bf16 v[6:9], v[148:151], v[188:191], v[6:9]
	v_mfma_f32_16x16x32_bf16 v[2:5], v[156:159], v[188:191], v[2:5]
	v_mfma_f32_16x16x32_bf16 v[60:63], v[152:155], v[168:171], v[60:63]
	v_mfma_f32_16x16x32_bf16 v[52:55], v[160:163], v[168:171], v[52:55]
	v_mfma_f32_16x16x32_bf16 v[44:47], v[152:155], v[176:179], v[44:47]
	v_mfma_f32_16x16x32_bf16 v[36:39], v[160:163], v[176:179], v[36:39]
	v_mfma_f32_16x16x32_bf16 v[22:25], v[152:155], v[184:187], v[22:25]
	v_mfma_f32_16x16x32_bf16 v[18:21], v[160:163], v[184:187], v[18:21]
	v_mfma_f32_16x16x32_bf16 v[6:9], v[152:155], v[250:253], v[6:9]
	v_mfma_f32_16x16x32_bf16 v[2:5], v[160:163], v[250:253], v[2:5]
	s_barrier
	s_add_u32 s70, s70, 0x10000
	s_addc_u32 s80, s80, 0
	s_add_u32 s8, s8, 0x100
	s_addc_u32 s9, s9, 0
	s_cmp_lt_i32 vcc_lo, s58
	s_mov_b32 s66, vcc_lo
	s_cbranch_scc1 .LBB0_324
	v_mov_b32_e32 v252, v212
	s_branch .LBB0_235

.LBB0_327:
	s_add_i32 s70, s8, 2
	s_add_u32 s9, s6, 0xfff00080
	s_addc_u32 s10, s7, -1
	s_add_i32 s34, 0, 0x10000
	s_cmp_eq_u32 s59, s8
	s_cselect_b32 s11, s65, s10
	s_cselect_b32 s10, s64, s9
	v_add_u32_e32 v0, s34, v217
	s_cselect_b32 s9, s53, s67
	s_cselect_b32 s8, s52, s66
	s_add_i32 s35, 0, 0x14000
	ds_read_b128 v[132:135], v0
	ds_read_b128 v[136:139], v0 offset:1024
	ds_read_b128 v[140:143], v0 offset:2048
	ds_read_b128 v[144:147], v0 offset:3072
	v_add_u32_e32 v0, s35, v217
	ds_read_b128 v[148:151], v0
	ds_read_b128 v[152:155], v0 offset:1024
	ds_read_b128 v[156:159], v0 offset:2048
	ds_read_b128 v[160:163], v0 offset:3072
	v_add_u32_e32 v0, 0, v216
	s_add_i32 m0, s29, 0xc000
	ds_read_b128 v[164:167], v0
	ds_read_b128 v[168:171], v0 offset:1024
	ds_read_b128 v[172:175], v0 offset:2048
	ds_read_b128 v[176:179], v0 offset:3072
	ds_read_b128 v[180:183], v0 offset:4096
	ds_read_b128 v[184:187], v0 offset:5120
	ds_read_b128 v[188:191], v0 offset:6144
	ds_read_b128 v[250:253], v0 offset:7168
	global_load_lds_dwordx4 v204, s[6:7]
	s_add_i32 m0, s29, 0xe000
	s_nop 0
	global_load_lds_dwordx4 v206, s[6:7]
	s_waitcnt vmcnt(8) lgkmcnt(0)
	s_barrier
	v_mfma_i32_16x16x64_i8 v[128:131], v[132:135], v[164:167], v[128:131]
	v_mfma_i32_16x16x64_i8 v[112:115], v[140:143], v[164:167], v[112:115]
	v_mfma_i32_16x16x64_i8 v[120:123], v[132:135], v[172:175], v[120:123]
	v_mfma_i32_16x16x64_i8 v[96:99], v[140:143], v[172:175], v[96:99]
	v_mfma_i32_16x16x64_i8 v[104:107], v[132:135], v[180:183], v[104:107]
	v_mfma_i32_16x16x64_i8 v[88:91], v[140:143], v[180:183], v[88:91]
	v_mfma_i32_16x16x64_i8 v[84:87], v[132:135], v[188:191], v[84:87]
	v_mfma_i32_16x16x64_i8 v[72:75], v[140:143], v[188:191], v[72:75]
	v_mfma_i32_16x16x64_i8 v[128:131], v[136:139], v[168:171], v[128:131]
	v_mfma_i32_16x16x64_i8 v[112:115], v[144:147], v[168:171], v[112:115]
	v_mfma_i32_16x16x64_i8 v[120:123], v[136:139], v[176:179], v[120:123]
	v_mfma_i32_16x16x64_i8 v[96:99], v[144:147], v[176:179], v[96:99]
	v_mfma_i32_16x16x64_i8 v[104:107], v[136:139], v[184:187], v[104:107]
	v_mfma_i32_16x16x64_i8 v[88:91], v[144:147], v[184:187], v[88:91]
	v_mfma_i32_16x16x64_i8 v[84:87], v[136:139], v[250:253], v[84:87]
	v_mfma_i32_16x16x64_i8 v[72:75], v[144:147], v[250:253], v[72:75]
	v_mfma_i32_16x16x64_i8 v[124:127], v[148:151], v[164:167], v[124:127]
	v_mfma_i32_16x16x64_i8 v[108:111], v[156:159], v[164:167], v[108:111]
	v_mfma_i32_16x16x64_i8 v[116:119], v[148:151], v[172:175], v[116:119]
	v_mfma_i32_16x16x64_i8 v[92:95], v[156:159], v[172:175], v[92:95]
	v_mfma_i32_16x16x64_i8 v[100:103], v[148:151], v[180:183], v[100:103]
	v_mfma_i32_16x16x64_i8 v[80:83], v[156:159], v[180:183], v[80:83]
	v_mfma_i32_16x16x64_i8 v[76:79], v[148:151], v[188:191], v[76:79]
	v_mfma_i32_16x16x64_i8 v[68:71], v[156:159], v[188:191], v[68:71]
	v_mfma_i32_16x16x64_i8 v[124:127], v[152:155], v[168:171], v[124:127]
	v_mfma_i32_16x16x64_i8 v[108:111], v[160:163], v[168:171], v[108:111]
	v_mfma_i32_16x16x64_i8 v[116:119], v[152:155], v[176:179], v[116:119]
	v_mfma_i32_16x16x64_i8 v[92:95], v[160:163], v[176:179], v[92:95]
	v_mfma_i32_16x16x64_i8 v[100:103], v[152:155], v[184:187], v[100:103]
	v_mfma_i32_16x16x64_i8 v[80:83], v[160:163], v[184:187], v[80:83]
	v_mfma_i32_16x16x64_i8 v[76:79], v[152:155], v[250:253], v[76:79]
	v_mfma_i32_16x16x64_i8 v[68:71], v[160:163], v[250:253], v[68:71]
	s_barrier
	s_add_i32 s34, s34, s0
	s_mov_b32 m0, s34
	ds_read_b128 v[164:167], v0 offset:16384
	ds_read_b128 v[168:171], v0 offset:17408
	ds_read_b128 v[172:175], v0 offset:18432
	ds_read_b128 v[176:179], v0 offset:19456
	ds_read_b128 v[180:183], v0 offset:20480
	ds_read_b128 v[184:187], v0 offset:21504
	ds_read_b128 v[188:191], v0 offset:22528
	ds_read_b128 v[250:253], v0 offset:23552
	global_load_lds_dwordx4 v196, s[8:9]
	s_add_i32 m0, s34, 0x2000
	s_add_u32 s94, s8, 0x4000
	s_addc_u32 s95, s9, 0
	s_add_i32 s34, s35, s0
	global_load_lds_dwordx4 v200, s[8:9]
	s_mov_b32 m0, s34
	v_lshl_add_u64 v[194:195], s[10:11], 0, v[202:203]
	global_load_lds_dwordx4 v196, s[94:95]
	s_add_i32 m0, s34, 0x2000
	s_nop 0
	global_load_lds_dwordx4 v200, s[94:95]
	v_lshl_add_u64 v[192:193], s[10:11], 0, v[198:199]
	s_waitcnt vmcnt(6) lgkmcnt(0)
	s_barrier
	v_mfma_i32_16x16x64_i8 v[64:67], v[132:135], v[164:167], v[64:67]
	v_mfma_i32_16x16x64_i8 v[56:59], v[140:143], v[164:167], v[56:59]
	v_mfma_i32_16x16x64_i8 v[48:51], v[132:135], v[172:175], v[48:51]
	v_mfma_i32_16x16x64_i8 v[40:43], v[140:143], v[172:175], v[40:43]
	v_mfma_i32_16x16x64_i8 v[30:33], v[132:135], v[180:183], v[30:33]
	v_mfma_i32_16x16x64_i8 v[26:29], v[140:143], v[180:183], v[26:29]
	v_mfma_i32_16x16x64_i8 v[14:17], v[132:135], v[188:191], v[14:17]
	v_mfma_i32_16x16x64_i8 v[10:13], v[140:143], v[188:191], v[10:13]
	v_mfma_i32_16x16x64_i8 v[64:67], v[136:139], v[168:171], v[64:67]
	v_mfma_i32_16x16x64_i8 v[56:59], v[144:147], v[168:171], v[56:59]
	v_mfma_i32_16x16x64_i8 v[48:51], v[136:139], v[176:179], v[48:51]
	v_mfma_i32_16x16x64_i8 v[40:43], v[144:147], v[176:179], v[40:43]
	v_mfma_i32_16x16x64_i8 v[30:33], v[136:139], v[184:187], v[30:33]
	v_mfma_i32_16x16x64_i8 v[26:29], v[144:147], v[184:187], v[26:29]
	v_mfma_i32_16x16x64_i8 v[14:17], v[136:139], v[250:253], v[14:17]
	v_mfma_i32_16x16x64_i8 v[10:13], v[144:147], v[250:253], v[10:13]
	v_mfma_i32_16x16x64_i8 v[60:63], v[148:151], v[164:167], v[60:63]
	v_mfma_i32_16x16x64_i8 v[52:55], v[156:159], v[164:167], v[52:55]
	v_mfma_i32_16x16x64_i8 v[44:47], v[148:151], v[172:175], v[44:47]
	v_mfma_i32_16x16x64_i8 v[36:39], v[156:159], v[172:175], v[36:39]
	v_mfma_i32_16x16x64_i8 v[22:25], v[148:151], v[180:183], v[22:25]
	v_mfma_i32_16x16x64_i8 v[18:21], v[156:159], v[180:183], v[18:21]
	v_mfma_i32_16x16x64_i8 v[6:9], v[148:151], v[188:191], v[6:9]
	v_mfma_i32_16x16x64_i8 v[2:5], v[156:159], v[188:191], v[2:5]
	v_mfma_i32_16x16x64_i8 v[60:63], v[152:155], v[168:171], v[60:63]
	v_mfma_i32_16x16x64_i8 v[52:55], v[160:163], v[168:171], v[52:55]
	v_mfma_i32_16x16x64_i8 v[44:47], v[152:155], v[176:179], v[44:47]
	v_mfma_i32_16x16x64_i8 v[36:39], v[160:163], v[176:179], v[36:39]
	v_mfma_i32_16x16x64_i8 v[22:25], v[152:155], v[184:187], v[22:25]
	v_mfma_i32_16x16x64_i8 v[18:21], v[160:163], v[184:187], v[18:21]
	v_mfma_i32_16x16x64_i8 v[6:9], v[152:155], v[250:253], v[6:9]
	v_mfma_i32_16x16x64_i8 v[2:5], v[160:163], v[250:253], v[2:5]
	s_barrier
	s_mov_b32 m0, s29
	s_nop 0
	global_load_lds_dwordx4 v198, s[10:11]
	s_mov_b32 m0, s45
	s_nop 0
	global_load_lds_dwordx4 v202, s[10:11]
	s_add_i32 s34, 0, 0x18000
	s_add_i32 s35, 0, 0x1c000
	v_add_u32_e32 v144, s34, v217
	v_add_u32_e32 v160, s35, v217
	ds_read_b128 v[132:135], v144
	ds_read_b128 v[136:139], v144 offset:1024
	ds_read_b128 v[140:143], v144 offset:2048
	ds_read_b128 v[144:147], v144 offset:3072
	ds_read_b128 v[148:151], v160
	ds_read_b128 v[152:155], v160 offset:1024
	ds_read_b128 v[156:159], v160 offset:2048
	ds_read_b128 v[160:163], v160 offset:3072
	s_add_u32 s10, s10, 0x100000
	s_addc_u32 s11, s11, 0
	s_mov_b32 m0, s82
	ds_read_b128 v[164:167], v0 offset:32768
	ds_read_b128 v[168:171], v0 offset:33792
	ds_read_b128 v[172:175], v0 offset:34816
	ds_read_b128 v[176:179], v0 offset:35840
	ds_read_b128 v[180:183], v0 offset:36864
	ds_read_b128 v[184:187], v0 offset:37888
	ds_read_b128 v[188:191], v0 offset:38912
	ds_read_b128 v[250:253], v0 offset:39936
	global_load_lds_dwordx4 v198, s[10:11]
	s_mov_b32 m0, s90
	s_nop 0
	global_load_lds_dwordx4 v202, s[10:11]
	s_waitcnt vmcnt(8) lgkmcnt(0)
	s_barrier
	v_mfma_i32_16x16x64_i8 v[128:131], v[132:135], v[164:167], v[128:131]
	v_mfma_i32_16x16x64_i8 v[112:115], v[140:143], v[164:167], v[112:115]
	v_mfma_i32_16x16x64_i8 v[120:123], v[132:135], v[172:175], v[120:123]
	v_mfma_i32_16x16x64_i8 v[96:99], v[140:143], v[172:175], v[96:99]
	v_mfma_i32_16x16x64_i8 v[104:107], v[132:135], v[180:183], v[104:107]
	v_mfma_i32_16x16x64_i8 v[88:91], v[140:143], v[180:183], v[88:91]
	v_mfma_i32_16x16x64_i8 v[84:87], v[132:135], v[188:191], v[84:87]
	v_mfma_i32_16x16x64_i8 v[72:75], v[140:143], v[188:191], v[72:75]
	v_mfma_i32_16x16x64_i8 v[128:131], v[136:139], v[168:171], v[128:131]
	v_mfma_i32_16x16x64_i8 v[112:115], v[144:147], v[168:171], v[112:115]
	v_mfma_i32_16x16x64_i8 v[120:123], v[136:139], v[176:179], v[120:123]
	v_mfma_i32_16x16x64_i8 v[96:99], v[144:147], v[176:179], v[96:99]
	v_mfma_i32_16x16x64_i8 v[104:107], v[136:139], v[184:187], v[104:107]
	v_mfma_i32_16x16x64_i8 v[88:91], v[144:147], v[184:187], v[88:91]
	v_mfma_i32_16x16x64_i8 v[84:87], v[136:139], v[250:253], v[84:87]
	v_mfma_i32_16x16x64_i8 v[72:75], v[144:147], v[250:253], v[72:75]
	v_mfma_i32_16x16x64_i8 v[124:127], v[148:151], v[164:167], v[124:127]
	v_mfma_i32_16x16x64_i8 v[108:111], v[156:159], v[164:167], v[108:111]
	v_mfma_i32_16x16x64_i8 v[116:119], v[148:151], v[172:175], v[116:119]
	v_mfma_i32_16x16x64_i8 v[92:95], v[156:159], v[172:175], v[92:95]
	v_mfma_i32_16x16x64_i8 v[100:103], v[148:151], v[180:183], v[100:103]
	v_mfma_i32_16x16x64_i8 v[80:83], v[156:159], v[180:183], v[80:83]
	v_mfma_i32_16x16x64_i8 v[76:79], v[148:151], v[188:191], v[76:79]
	v_mfma_i32_16x16x64_i8 v[68:71], v[156:159], v[188:191], v[68:71]
	v_mfma_i32_16x16x64_i8 v[124:127], v[152:155], v[168:171], v[124:127]
	v_mfma_i32_16x16x64_i8 v[108:111], v[160:163], v[168:171], v[108:111]
	v_mfma_i32_16x16x64_i8 v[116:119], v[152:155], v[176:179], v[116:119]
	v_mfma_i32_16x16x64_i8 v[92:95], v[160:163], v[176:179], v[92:95]
	v_mfma_i32_16x16x64_i8 v[100:103], v[152:155], v[184:187], v[100:103]
	v_mfma_i32_16x16x64_i8 v[80:83], v[160:163], v[184:187], v[80:83]
	v_mfma_i32_16x16x64_i8 v[76:79], v[152:155], v[250:253], v[76:79]
	v_mfma_i32_16x16x64_i8 v[68:71], v[160:163], v[250:253], v[68:71]
	s_barrier
	s_add_u32 s10, s8, 0x8000
	s_addc_u32 s11, s9, 0
	s_add_i32 s34, s34, s0
	s_mov_b32 m0, s34
	ds_read_b128 v[164:167], v0 offset:49152
	ds_read_b128 v[168:171], v0 offset:50176
	ds_read_b128 v[172:175], v0 offset:51200
	ds_read_b128 v[176:179], v0 offset:52224
	ds_read_b128 v[180:183], v0 offset:53248
	ds_read_b128 v[184:187], v0 offset:54272
	ds_read_b128 v[188:191], v0 offset:55296
	ds_read_b128 v[250:253], v0 offset:56320
	global_load_lds_dwordx4 v196, s[10:11]
	s_add_i32 m0, s34, 0x2000
	s_add_u32 s8, s8, 0xc000
	v_lshl_add_u64 v[210:211], s[10:11], 0, v[200:201]
	s_addc_u32 s9, s9, 0
	s_add_i32 s10, s35, s0
	global_load_lds_dwordx4 v[210:211], off
	s_mov_b32 m0, s10
	v_lshl_add_u64 v[192:193], v[192:193], 0, s[92:93]
	global_load_lds_dwordx4 v196, s[8:9]
	s_add_i32 m0, s10, 0x2000
	s_nop 0
	global_load_lds_dwordx4 v200, s[8:9]
	s_mov_b32 m0, s91
	s_nop 0
	global_load_lds_dwordx4 v[192:193], off
	v_lshl_add_u64 v[192:193], v[194:195], 0, s[92:93]
	s_mov_b32 m0, s30
	s_nop 0
	global_load_lds_dwordx4 v[192:193], off
	s_waitcnt vmcnt(8) lgkmcnt(0)
	s_barrier
	v_mfma_i32_16x16x64_i8 v[64:67], v[132:135], v[164:167], v[64:67]
	v_mfma_i32_16x16x64_i8 v[56:59], v[140:143], v[164:167], v[56:59]
	v_mfma_i32_16x16x64_i8 v[48:51], v[132:135], v[172:175], v[48:51]
	v_mfma_i32_16x16x64_i8 v[40:43], v[140:143], v[172:175], v[40:43]
	v_mfma_i32_16x16x64_i8 v[30:33], v[132:135], v[180:183], v[30:33]
	v_mfma_i32_16x16x64_i8 v[26:29], v[140:143], v[180:183], v[26:29]
	v_mfma_i32_16x16x64_i8 v[14:17], v[132:135], v[188:191], v[14:17]
	v_mfma_i32_16x16x64_i8 v[10:13], v[140:143], v[188:191], v[10:13]
	v_mfma_i32_16x16x64_i8 v[64:67], v[136:139], v[168:171], v[64:67]
	v_mfma_i32_16x16x64_i8 v[56:59], v[144:147], v[168:171], v[56:59]
	v_mfma_i32_16x16x64_i8 v[48:51], v[136:139], v[176:179], v[48:51]
	v_mfma_i32_16x16x64_i8 v[40:43], v[144:147], v[176:179], v[40:43]
	v_mfma_i32_16x16x64_i8 v[30:33], v[136:139], v[184:187], v[30:33]
	v_mfma_i32_16x16x64_i8 v[26:29], v[144:147], v[184:187], v[26:29]
	v_mfma_i32_16x16x64_i8 v[14:17], v[136:139], v[250:253], v[14:17]
	v_mfma_i32_16x16x64_i8 v[10:13], v[144:147], v[250:253], v[10:13]
	v_mfma_i32_16x16x64_i8 v[60:63], v[148:151], v[164:167], v[60:63]
	v_mfma_i32_16x16x64_i8 v[52:55], v[156:159], v[164:167], v[52:55]
	v_mfma_i32_16x16x64_i8 v[44:47], v[148:151], v[172:175], v[44:47]
	v_mfma_i32_16x16x64_i8 v[36:39], v[156:159], v[172:175], v[36:39]
	v_mfma_i32_16x16x64_i8 v[22:25], v[148:151], v[180:183], v[22:25]
	v_mfma_i32_16x16x64_i8 v[18:21], v[156:159], v[180:183], v[18:21]
	v_mfma_i32_16x16x64_i8 v[6:9], v[148:151], v[188:191], v[6:9]
	v_mfma_i32_16x16x64_i8 v[2:5], v[156:159], v[188:191], v[2:5]
	v_mfma_i32_16x16x64_i8 v[60:63], v[152:155], v[168:171], v[60:63]
	v_mfma_i32_16x16x64_i8 v[52:55], v[160:163], v[168:171], v[52:55]
	v_mfma_i32_16x16x64_i8 v[44:47], v[152:155], v[176:179], v[44:47]
	v_mfma_i32_16x16x64_i8 v[36:39], v[160:163], v[176:179], v[36:39]
	v_mfma_i32_16x16x64_i8 v[22:25], v[152:155], v[184:187], v[22:25]
	v_mfma_i32_16x16x64_i8 v[18:21], v[160:163], v[184:187], v[18:21]
	v_mfma_i32_16x16x64_i8 v[6:9], v[152:155], v[250:253], v[6:9]
	v_mfma_i32_16x16x64_i8 v[2:5], v[160:163], v[250:253], v[2:5]
	s_barrier
	s_add_u32 s66, s66, 0x10000
	s_addc_u32 s67, s67, 0
	s_add_u32 s6, s6, 0x100
	s_addc_u32 s7, s7, 0
	s_cmp_ge_i32 s70, s58
	s_mov_b32 s8, s70
	s_cbranch_scc0 .LBB0_327
	v_mov_b32_e32 v252, v212
	v_cndmask_b32_e64 v0, 0, 1, s[46:47]
	v_cmp_ne_u32_e64 s[6:7], 1, v0
	s_andn2_b64 vcc, exec, s[46:47]
	s_cbranch_vccz .LBB0_236
	s_branch .LBB0_237

.LBB0_707:
	s_add_u32 s34, s50, 0xfff80080
	s_addc_u32 s35, s51, -1
	s_add_i32 s61, 0, 0x10000
	s_cmp_eq_u32 s60, 4
	s_cselect_b32 s55, s23, s35
	s_cselect_b32 s54, s22, s34
	s_cselect_b32 s53, s43, s59
	s_cselect_b32 s52, s42, s21
	s_add_i32 s62, 0, 0x14000
	ds_read_b128 v[164:167], v2 offset:0
	ds_read_b128 v[168:171], v2 offset:1024
	ds_read_b128 v[172:175], v2 offset:2048
	ds_read_b128 v[176:179], v2 offset:3072
	ds_read_b128 v[192:195], v2 offset:16384
	ds_read_b128 v[196:199], v2 offset:17408
	ds_read_b128 v[204:207], v2 offset:18432
	ds_read_b128 v[210:213], v2 offset:19456
	s_add_i32 m0, s29, 0xc000
	ds_read_b128 v[216:219], v203
	ds_read_b128 v[220:223], v203 offset:1024
	ds_read_b128 v[224:227], v203 offset:2048
	ds_read_b128 v[228:231], v203 offset:3072
	ds_read_b128 v[232:235], v203 offset:4096
	ds_read_b128 v[236:239], v203 offset:5120
	ds_read_b128 v[240:243], v203 offset:6144
	ds_read_b128 v[244:247], v203 offset:7168
	global_load_lds_dwordx4 v188, s[50:51]
	s_add_i32 m0, s29, 0xe000
	s_nop 0
	global_load_lds_dwordx4 v190, s[50:51]
	s_waitcnt vmcnt(8) lgkmcnt(0)
	s_barrier
	v_mfma_f32_16x16x32_bf16 v[160:163], v[164:167], v[216:219], v[160:163]
	v_mfma_f32_16x16x32_bf16 v[156:159], v[172:175], v[216:219], v[156:159]
	v_mfma_f32_16x16x32_bf16 v[144:147], v[164:167], v[224:227], v[144:147]
	v_mfma_f32_16x16x32_bf16 v[140:143], v[172:175], v[224:227], v[140:143]
	v_mfma_f32_16x16x32_bf16 v[128:131], v[164:167], v[232:235], v[128:131]
	v_mfma_f32_16x16x32_bf16 v[124:127], v[172:175], v[232:235], v[124:127]
	v_mfma_f32_16x16x32_bf16 v[112:115], v[164:167], v[240:243], v[112:115]
	v_mfma_f32_16x16x32_bf16 v[108:111], v[172:175], v[240:243], v[108:111]
	v_mfma_f32_16x16x32_bf16 v[160:163], v[168:171], v[220:223], v[160:163]
	v_mfma_f32_16x16x32_bf16 v[156:159], v[176:179], v[220:223], v[156:159]
	v_mfma_f32_16x16x32_bf16 v[144:147], v[168:171], v[228:231], v[144:147]
	v_mfma_f32_16x16x32_bf16 v[140:143], v[176:179], v[228:231], v[140:143]
	v_mfma_f32_16x16x32_bf16 v[128:131], v[168:171], v[236:239], v[128:131]
	v_mfma_f32_16x16x32_bf16 v[124:127], v[176:179], v[236:239], v[124:127]
	v_mfma_f32_16x16x32_bf16 v[112:115], v[168:171], v[244:247], v[112:115]
	v_mfma_f32_16x16x32_bf16 v[108:111], v[176:179], v[244:247], v[108:111]
	v_mfma_f32_16x16x32_bf16 v[152:155], v[192:195], v[216:219], v[152:155]
	v_mfma_f32_16x16x32_bf16 v[148:151], v[204:207], v[216:219], v[148:151]
	v_mfma_f32_16x16x32_bf16 v[136:139], v[192:195], v[224:227], v[136:139]
	v_mfma_f32_16x16x32_bf16 v[132:135], v[204:207], v[224:227], v[132:135]
	v_mfma_f32_16x16x32_bf16 v[120:123], v[192:195], v[232:235], v[120:123]
	v_mfma_f32_16x16x32_bf16 v[116:119], v[204:207], v[232:235], v[116:119]
	v_mfma_f32_16x16x32_bf16 v[104:107], v[192:195], v[240:243], v[104:107]
	v_mfma_f32_16x16x32_bf16 v[100:103], v[204:207], v[240:243], v[100:103]
	v_mfma_f32_16x16x32_bf16 v[152:155], v[196:199], v[220:223], v[152:155]
	v_mfma_f32_16x16x32_bf16 v[148:151], v[210:213], v[220:223], v[148:151]
	v_mfma_f32_16x16x32_bf16 v[136:139], v[196:199], v[228:231], v[136:139]
	v_mfma_f32_16x16x32_bf16 v[132:135], v[210:213], v[228:231], v[132:135]
	v_mfma_f32_16x16x32_bf16 v[120:123], v[196:199], v[236:239], v[120:123]
	v_mfma_f32_16x16x32_bf16 v[116:119], v[210:213], v[236:239], v[116:119]
	v_mfma_f32_16x16x32_bf16 v[104:107], v[196:199], v[244:247], v[104:107]
	v_mfma_f32_16x16x32_bf16 v[100:103], v[210:213], v[244:247], v[100:103]
	s_barrier
	s_add_i32 s34, s61, s0
	s_mov_b32 m0, s34
	ds_read_b128 v[216:219], v203 offset:16384
	ds_read_b128 v[220:223], v203 offset:17408
	ds_read_b128 v[224:227], v203 offset:18432
	ds_read_b128 v[228:231], v203 offset:19456
	ds_read_b128 v[232:235], v203 offset:20480
	ds_read_b128 v[236:239], v203 offset:21504
	ds_read_b128 v[240:243], v203 offset:22528
	ds_read_b128 v[244:247], v203 offset:23552
	global_load_lds_dwordx4 v180, s[52:53]
	s_add_i32 m0, s34, 0x2000
	s_add_u32 s34, s52, 0x4000
	s_addc_u32 s35, s53, 0
	s_add_i32 s61, s62, s0
	global_load_lds_dwordx4 v184, s[52:53]
	s_mov_b32 m0, s61
	v_lshl_add_u64 v[248:249], s[54:55], 0, v[186:187]
	global_load_lds_dwordx4 v180, s[34:35]
	s_add_i32 m0, s61, 0x2000
	s_nop 0
	global_load_lds_dwordx4 v184, s[34:35]
	v_lshl_add_u64 v[200:201], s[54:55], 0, v[182:183]
	s_waitcnt vmcnt(6) lgkmcnt(0)
	s_barrier
	v_mfma_f32_16x16x32_bf16 v[96:99], v[164:167], v[216:219], v[96:99]
	v_mfma_f32_16x16x32_bf16 v[92:95], v[172:175], v[216:219], v[92:95]
	v_mfma_f32_16x16x32_bf16 v[84:87], v[164:167], v[224:227], v[84:87]
	v_mfma_f32_16x16x32_bf16 v[76:79], v[172:175], v[224:227], v[76:79]
	v_mfma_f32_16x16x32_bf16 v[68:71], v[164:167], v[232:235], v[68:71]
	v_mfma_f32_16x16x32_bf16 v[60:63], v[172:175], v[232:235], v[60:63]
	v_mfma_f32_16x16x32_bf16 v[52:55], v[164:167], v[240:243], v[52:55]
	v_mfma_f32_16x16x32_bf16 v[44:47], v[172:175], v[240:243], v[44:47]
	v_mfma_f32_16x16x32_bf16 v[96:99], v[168:171], v[220:223], v[96:99]
	v_mfma_f32_16x16x32_bf16 v[92:95], v[176:179], v[220:223], v[92:95]
	v_mfma_f32_16x16x32_bf16 v[84:87], v[168:171], v[228:231], v[84:87]
	v_mfma_f32_16x16x32_bf16 v[76:79], v[176:179], v[228:231], v[76:79]
	v_mfma_f32_16x16x32_bf16 v[68:71], v[168:171], v[236:239], v[68:71]
	v_mfma_f32_16x16x32_bf16 v[60:63], v[176:179], v[236:239], v[60:63]
	v_mfma_f32_16x16x32_bf16 v[52:55], v[168:171], v[244:247], v[52:55]
	v_mfma_f32_16x16x32_bf16 v[44:47], v[176:179], v[244:247], v[44:47]
	v_mfma_f32_16x16x32_bf16 v[88:91], v[192:195], v[216:219], v[88:91]
	v_mfma_f32_16x16x32_bf16 v[80:83], v[204:207], v[216:219], v[80:83]
	v_mfma_f32_16x16x32_bf16 v[72:75], v[192:195], v[224:227], v[72:75]
	v_mfma_f32_16x16x32_bf16 v[64:67], v[204:207], v[224:227], v[64:67]
	v_mfma_f32_16x16x32_bf16 v[56:59], v[192:195], v[232:235], v[56:59]
	v_mfma_f32_16x16x32_bf16 v[48:51], v[204:207], v[232:235], v[48:51]
	v_mfma_f32_16x16x32_bf16 v[40:43], v[192:195], v[240:243], v[40:43]
	v_mfma_f32_16x16x32_bf16 v[36:39], v[204:207], v[240:243], v[36:39]
	v_mfma_f32_16x16x32_bf16 v[88:91], v[196:199], v[220:223], v[88:91]
	v_mfma_f32_16x16x32_bf16 v[80:83], v[210:213], v[220:223], v[80:83]
	v_mfma_f32_16x16x32_bf16 v[72:75], v[196:199], v[228:231], v[72:75]
	v_mfma_f32_16x16x32_bf16 v[64:67], v[210:213], v[228:231], v[64:67]
	v_mfma_f32_16x16x32_bf16 v[56:59], v[196:199], v[236:239], v[56:59]
	v_mfma_f32_16x16x32_bf16 v[48:51], v[210:213], v[236:239], v[48:51]
	v_mfma_f32_16x16x32_bf16 v[40:43], v[196:199], v[244:247], v[40:43]
	v_mfma_f32_16x16x32_bf16 v[36:39], v[210:213], v[244:247], v[36:39]
	s_barrier
	s_mov_b32 m0, s29
	s_nop 0
	global_load_lds_dwordx4 v182, s[54:55]
	s_mov_b32 m0, s45
	s_nop 0
	global_load_lds_dwordx4 v186, s[54:55]
	s_add_i32 s61, 0, 0x18000
	s_add_i32 s62, 0, 0x1c000
	ds_read_b128 v[164:167], v2 offset:32768
	ds_read_b128 v[168:171], v2 offset:33792
	ds_read_b128 v[172:175], v2 offset:34816
	ds_read_b128 v[176:179], v2 offset:35840
	ds_read_b128 v[192:195], v2 offset:49152
	ds_read_b128 v[196:199], v2 offset:50176
	ds_read_b128 v[204:207], v2 offset:51200
	ds_read_b128 v[210:213], v2 offset:52224
	s_add_u32 s34, s54, 0x80000
	s_addc_u32 s35, s55, 0
	s_mov_b32 m0, s82
	ds_read_b128 v[216:219], v203 offset:32768
	ds_read_b128 v[220:223], v203 offset:33792
	ds_read_b128 v[224:227], v203 offset:34816
	ds_read_b128 v[228:231], v203 offset:35840
	ds_read_b128 v[232:235], v203 offset:36864
	ds_read_b128 v[236:239], v203 offset:37888
	ds_read_b128 v[240:243], v203 offset:38912
	ds_read_b128 v[244:247], v203 offset:39936
	global_load_lds_dwordx4 v182, s[34:35]
	s_mov_b32 m0, s90
	s_nop 0
	global_load_lds_dwordx4 v186, s[34:35]
	s_waitcnt vmcnt(8) lgkmcnt(0)
	s_barrier
	v_mfma_f32_16x16x32_bf16 v[160:163], v[164:167], v[216:219], v[160:163]
	v_mfma_f32_16x16x32_bf16 v[156:159], v[172:175], v[216:219], v[156:159]
	v_mfma_f32_16x16x32_bf16 v[144:147], v[164:167], v[224:227], v[144:147]
	v_mfma_f32_16x16x32_bf16 v[140:143], v[172:175], v[224:227], v[140:143]
	v_mfma_f32_16x16x32_bf16 v[128:131], v[164:167], v[232:235], v[128:131]
	v_mfma_f32_16x16x32_bf16 v[124:127], v[172:175], v[232:235], v[124:127]
	v_mfma_f32_16x16x32_bf16 v[112:115], v[164:167], v[240:243], v[112:115]
	v_mfma_f32_16x16x32_bf16 v[108:111], v[172:175], v[240:243], v[108:111]
	v_mfma_f32_16x16x32_bf16 v[160:163], v[168:171], v[220:223], v[160:163]
	v_mfma_f32_16x16x32_bf16 v[156:159], v[176:179], v[220:223], v[156:159]
	v_mfma_f32_16x16x32_bf16 v[144:147], v[168:171], v[228:231], v[144:147]
	v_mfma_f32_16x16x32_bf16 v[140:143], v[176:179], v[228:231], v[140:143]
	v_mfma_f32_16x16x32_bf16 v[128:131], v[168:171], v[236:239], v[128:131]
	v_mfma_f32_16x16x32_bf16 v[124:127], v[176:179], v[236:239], v[124:127]
	v_mfma_f32_16x16x32_bf16 v[112:115], v[168:171], v[244:247], v[112:115]
	v_mfma_f32_16x16x32_bf16 v[108:111], v[176:179], v[244:247], v[108:111]
	v_mfma_f32_16x16x32_bf16 v[152:155], v[192:195], v[216:219], v[152:155]
	v_mfma_f32_16x16x32_bf16 v[148:151], v[204:207], v[216:219], v[148:151]
	v_mfma_f32_16x16x32_bf16 v[136:139], v[192:195], v[224:227], v[136:139]
	v_mfma_f32_16x16x32_bf16 v[132:135], v[204:207], v[224:227], v[132:135]
	v_mfma_f32_16x16x32_bf16 v[120:123], v[192:195], v[232:235], v[120:123]
	v_mfma_f32_16x16x32_bf16 v[116:119], v[204:207], v[232:235], v[116:119]
	v_mfma_f32_16x16x32_bf16 v[104:107], v[192:195], v[240:243], v[104:107]
	v_mfma_f32_16x16x32_bf16 v[100:103], v[204:207], v[240:243], v[100:103]
	v_mfma_f32_16x16x32_bf16 v[152:155], v[196:199], v[220:223], v[152:155]
	v_mfma_f32_16x16x32_bf16 v[148:151], v[210:213], v[220:223], v[148:151]
	v_mfma_f32_16x16x32_bf16 v[136:139], v[196:199], v[228:231], v[136:139]
	v_mfma_f32_16x16x32_bf16 v[132:135], v[210:213], v[228:231], v[132:135]
	v_mfma_f32_16x16x32_bf16 v[120:123], v[196:199], v[236:239], v[120:123]
	v_mfma_f32_16x16x32_bf16 v[116:119], v[210:213], v[236:239], v[116:119]
	v_mfma_f32_16x16x32_bf16 v[104:107], v[196:199], v[244:247], v[104:107]
	v_mfma_f32_16x16x32_bf16 v[100:103], v[210:213], v[244:247], v[100:103]
	s_barrier
	s_add_u32 s34, s52, 0x8000
	s_addc_u32 s35, s53, 0
	s_add_i32 s54, s61, s0
	s_mov_b32 m0, s54
	ds_read_b128 v[216:219], v203 offset:49152
	ds_read_b128 v[220:223], v203 offset:50176
	ds_read_b128 v[224:227], v203 offset:51200
	ds_read_b128 v[228:231], v203 offset:52224
	ds_read_b128 v[232:235], v203 offset:53248
	ds_read_b128 v[236:239], v203 offset:54272
	ds_read_b128 v[240:243], v203 offset:55296
	ds_read_b128 v[244:247], v203 offset:56320
	global_load_lds_dwordx4 v180, s[34:35]
	s_add_i32 m0, s54, 0x2000
	v_lshl_add_u64 v[250:251], s[34:35], 0, v[184:185]
	s_add_u32 s34, s52, 0xc000
	s_addc_u32 s35, s53, 0
	s_add_i32 s52, s62, s0
	global_load_lds_dwordx4 v[250:251], off
	s_mov_b32 m0, s52
	v_lshl_add_u64 v[200:201], v[200:201], 0, s[92:93]
	global_load_lds_dwordx4 v180, s[34:35]
	s_add_i32 m0, s52, 0x2000
	s_nop 0
	global_load_lds_dwordx4 v184, s[34:35]
	s_mov_b32 m0, s91
	s_nop 0
	global_load_lds_dwordx4 v[200:201], off
	v_lshl_add_u64 v[200:201], v[248:249], 0, s[92:93]
	s_mov_b32 m0, s30
	s_nop 0
	global_load_lds_dwordx4 v[200:201], off
	s_waitcnt vmcnt(8) lgkmcnt(0)
	s_barrier
	v_mfma_f32_16x16x32_bf16 v[96:99], v[164:167], v[216:219], v[96:99]
	v_mfma_f32_16x16x32_bf16 v[92:95], v[172:175], v[216:219], v[92:95]
	v_mfma_f32_16x16x32_bf16 v[84:87], v[164:167], v[224:227], v[84:87]
	v_mfma_f32_16x16x32_bf16 v[76:79], v[172:175], v[224:227], v[76:79]
	v_mfma_f32_16x16x32_bf16 v[68:71], v[164:167], v[232:235], v[68:71]
	v_mfma_f32_16x16x32_bf16 v[60:63], v[172:175], v[232:235], v[60:63]
	v_mfma_f32_16x16x32_bf16 v[52:55], v[164:167], v[240:243], v[52:55]
	v_mfma_f32_16x16x32_bf16 v[44:47], v[172:175], v[240:243], v[44:47]
	v_mfma_f32_16x16x32_bf16 v[96:99], v[168:171], v[220:223], v[96:99]
	v_mfma_f32_16x16x32_bf16 v[92:95], v[176:179], v[220:223], v[92:95]
	v_mfma_f32_16x16x32_bf16 v[84:87], v[168:171], v[228:231], v[84:87]
	v_mfma_f32_16x16x32_bf16 v[76:79], v[176:179], v[228:231], v[76:79]
	v_mfma_f32_16x16x32_bf16 v[68:71], v[168:171], v[236:239], v[68:71]
	v_mfma_f32_16x16x32_bf16 v[60:63], v[176:179], v[236:239], v[60:63]
	v_mfma_f32_16x16x32_bf16 v[52:55], v[168:171], v[244:247], v[52:55]
	v_mfma_f32_16x16x32_bf16 v[44:47], v[176:179], v[244:247], v[44:47]
	v_mfma_f32_16x16x32_bf16 v[88:91], v[192:195], v[216:219], v[88:91]
	v_mfma_f32_16x16x32_bf16 v[80:83], v[204:207], v[216:219], v[80:83]
	v_mfma_f32_16x16x32_bf16 v[72:75], v[192:195], v[224:227], v[72:75]
	v_mfma_f32_16x16x32_bf16 v[64:67], v[204:207], v[224:227], v[64:67]
	v_mfma_f32_16x16x32_bf16 v[56:59], v[192:195], v[232:235], v[56:59]
	v_mfma_f32_16x16x32_bf16 v[48:51], v[204:207], v[232:235], v[48:51]
	v_mfma_f32_16x16x32_bf16 v[40:43], v[192:195], v[240:243], v[40:43]
	v_mfma_f32_16x16x32_bf16 v[36:39], v[204:207], v[240:243], v[36:39]
	v_mfma_f32_16x16x32_bf16 v[88:91], v[196:199], v[220:223], v[88:91]
	v_mfma_f32_16x16x32_bf16 v[80:83], v[210:213], v[220:223], v[80:83]
	v_mfma_f32_16x16x32_bf16 v[72:75], v[196:199], v[228:231], v[72:75]
	v_mfma_f32_16x16x32_bf16 v[64:67], v[210:213], v[228:231], v[64:67]
	v_mfma_f32_16x16x32_bf16 v[56:59], v[196:199], v[236:239], v[56:59]
	v_mfma_f32_16x16x32_bf16 v[48:51], v[210:213], v[236:239], v[48:51]
	v_mfma_f32_16x16x32_bf16 v[40:43], v[196:199], v[244:247], v[40:43]
	v_mfma_f32_16x16x32_bf16 v[36:39], v[210:213], v[244:247], v[36:39]
	s_barrier
	s_add_i32 s60, s60, 2
	s_add_u32 s21, s21, 0x10000
	s_addc_u32 s59, s59, 0
	s_add_u32 s50, s50, 0x100
	s_addc_u32 s51, s51, 0
	s_cmp_gt_u32 s60, 5
	s_cbranch_scc0 .LBB0_707
	s_and_b64 vcc, exec, s[46:47]
	s_cbranch_vccz .LBB0_710
	s_barrier

.LBB0_788:
	s_add_u32 s34, s48, 0xfff80080
	s_addc_u32 s35, s49, -1
	s_add_i32 s57, 0, 0x10000
	s_cmp_eq_u32 s56, 28
	s_cselect_b32 s55, s23, s35
	s_cselect_b32 s54, s22, s34
	s_cselect_b32 s53, s43, s51
	s_cselect_b32 s52, s42, s15
	s_add_i32 s69, 0, 0x14000
	ds_read_b128 v[136:139], v200 offset:0
	ds_read_b128 v[140:143], v200 offset:1024
	ds_read_b128 v[144:147], v200 offset:2048
	ds_read_b128 v[148:151], v200 offset:3072
	ds_read_b128 v[152:155], v200 offset:16384
	ds_read_b128 v[156:159], v200 offset:17408
	ds_read_b128 v[160:163], v200 offset:18432
	ds_read_b128 v[174:177], v200 offset:19456
	s_add_i32 m0, s29, 0xc000
	ds_read_b128 v[178:181], v199
	ds_read_b128 v[182:185], v199 offset:1024
	ds_read_b128 v[186:189], v199 offset:2048
	ds_read_b128 v[190:193], v199 offset:3072
	ds_read_b128 v[194:197], v199 offset:4096
	ds_read_b128 v[210:213], v199 offset:5120
	ds_read_b128 v[240:243], v199 offset:6144
	ds_read_b128 v[244:247], v199 offset:7168
	global_load_lds_dwordx4 v170, s[48:49]
	s_add_i32 m0, s29, 0xe000
	s_nop 0
	global_load_lds_dwordx4 v172, s[48:49]
	s_waitcnt vmcnt(8) lgkmcnt(0)
	s_barrier
	v_mfma_f32_16x16x32_bf16 v[132:135], v[136:139], v[178:181], v[132:135]
	v_mfma_f32_16x16x32_bf16 v[128:131], v[144:147], v[178:181], v[128:131]
	v_mfma_f32_16x16x32_bf16 v[124:127], v[136:139], v[186:189], v[124:127]
	v_mfma_f32_16x16x32_bf16 v[120:123], v[144:147], v[186:189], v[120:123]
	v_mfma_f32_16x16x32_bf16 v[116:119], v[136:139], v[194:197], v[116:119]
	v_mfma_f32_16x16x32_bf16 v[112:115], v[144:147], v[194:197], v[112:115]
	v_mfma_f32_16x16x32_bf16 v[108:111], v[136:139], v[240:243], v[108:111]
	v_mfma_f32_16x16x32_bf16 v[104:107], v[144:147], v[240:243], v[104:107]
	v_mfma_f32_16x16x32_bf16 v[132:135], v[140:143], v[182:185], v[132:135]
	v_mfma_f32_16x16x32_bf16 v[128:131], v[148:151], v[182:185], v[128:131]
	v_mfma_f32_16x16x32_bf16 v[124:127], v[140:143], v[190:193], v[124:127]
	v_mfma_f32_16x16x32_bf16 v[120:123], v[148:151], v[190:193], v[120:123]
	v_mfma_f32_16x16x32_bf16 v[116:119], v[140:143], v[210:213], v[116:119]
	v_mfma_f32_16x16x32_bf16 v[112:115], v[148:151], v[210:213], v[112:115]
	v_mfma_f32_16x16x32_bf16 v[108:111], v[140:143], v[244:247], v[108:111]
	v_mfma_f32_16x16x32_bf16 v[104:107], v[148:151], v[244:247], v[104:107]
	v_mfma_f32_16x16x32_bf16 v[100:103], v[152:155], v[178:181], v[100:103]
	v_mfma_f32_16x16x32_bf16 v[96:99], v[160:163], v[178:181], v[96:99]
	v_mfma_f32_16x16x32_bf16 v[92:95], v[152:155], v[186:189], v[92:95]
	v_mfma_f32_16x16x32_bf16 v[88:91], v[160:163], v[186:189], v[88:91]
	v_mfma_f32_16x16x32_bf16 v[84:87], v[152:155], v[194:197], v[84:87]
	v_mfma_f32_16x16x32_bf16 v[80:83], v[160:163], v[194:197], v[80:83]
	v_mfma_f32_16x16x32_bf16 v[72:75], v[152:155], v[240:243], v[72:75]
	v_mfma_f32_16x16x32_bf16 v[64:67], v[160:163], v[240:243], v[64:67]
	v_mfma_f32_16x16x32_bf16 v[100:103], v[156:159], v[182:185], v[100:103]
	v_mfma_f32_16x16x32_bf16 v[96:99], v[174:177], v[182:185], v[96:99]
	v_mfma_f32_16x16x32_bf16 v[92:95], v[156:159], v[190:193], v[92:95]
	v_mfma_f32_16x16x32_bf16 v[88:91], v[174:177], v[190:193], v[88:91]
	v_mfma_f32_16x16x32_bf16 v[84:87], v[156:159], v[210:213], v[84:87]
	v_mfma_f32_16x16x32_bf16 v[80:83], v[174:177], v[210:213], v[80:83]
	v_mfma_f32_16x16x32_bf16 v[72:75], v[156:159], v[244:247], v[72:75]
	v_mfma_f32_16x16x32_bf16 v[64:67], v[174:177], v[244:247], v[64:67]
	s_barrier
	s_add_i32 s34, s57, s0
	s_mov_b32 m0, s34
	ds_read_b128 v[178:181], v199 offset:16384
	ds_read_b128 v[182:185], v199 offset:17408
	ds_read_b128 v[186:189], v199 offset:18432
	ds_read_b128 v[190:193], v199 offset:19456
	ds_read_b128 v[194:197], v199 offset:20480
	ds_read_b128 v[210:213], v199 offset:21504
	ds_read_b128 v[240:243], v199 offset:22528
	ds_read_b128 v[244:247], v199 offset:23552
	global_load_lds_dwordx4 v32, s[52:53]
	s_add_i32 m0, s34, 0x2000
	s_add_u32 s34, s52, 0x4000
	s_addc_u32 s35, s53, 0
	s_add_i32 s57, s69, s0
	global_load_lds_dwordx4 v166, s[52:53]
	s_mov_b32 m0, s57
	v_lshl_add_u64 v[248:249], s[54:55], 0, v[164:165]
	global_load_lds_dwordx4 v32, s[34:35]
	s_add_i32 m0, s57, 0x2000
	v_lshl_add_u64 v[250:251], s[54:55], 0, v[168:169]
	global_load_lds_dwordx4 v166, s[34:35]
	s_waitcnt vmcnt(6) lgkmcnt(0)
	s_barrier
	v_mfma_f32_16x16x32_bf16 v[76:79], v[136:139], v[178:181], v[76:79]
	v_mfma_f32_16x16x32_bf16 v[68:71], v[144:147], v[178:181], v[68:71]
	v_mfma_f32_16x16x32_bf16 v[60:63], v[136:139], v[186:189], v[60:63]
	v_mfma_f32_16x16x32_bf16 v[56:59], v[144:147], v[186:189], v[56:59]
	v_mfma_f32_16x16x32_bf16 v[52:55], v[136:139], v[194:197], v[52:55]
	v_mfma_f32_16x16x32_bf16 v[48:51], v[144:147], v[194:197], v[48:51]
	v_mfma_f32_16x16x32_bf16 v[44:47], v[136:139], v[240:243], v[44:47]
	v_mfma_f32_16x16x32_bf16 v[40:43], v[144:147], v[240:243], v[40:43]
	v_mfma_f32_16x16x32_bf16 v[76:79], v[140:143], v[182:185], v[76:79]
	v_mfma_f32_16x16x32_bf16 v[68:71], v[148:151], v[182:185], v[68:71]
	v_mfma_f32_16x16x32_bf16 v[60:63], v[140:143], v[190:193], v[60:63]
	v_mfma_f32_16x16x32_bf16 v[56:59], v[148:151], v[190:193], v[56:59]
	v_mfma_f32_16x16x32_bf16 v[52:55], v[140:143], v[210:213], v[52:55]
	v_mfma_f32_16x16x32_bf16 v[48:51], v[148:151], v[210:213], v[48:51]
	v_mfma_f32_16x16x32_bf16 v[44:47], v[140:143], v[244:247], v[44:47]
	v_mfma_f32_16x16x32_bf16 v[40:43], v[148:151], v[244:247], v[40:43]
	v_mfma_f32_16x16x32_bf16 v[36:39], v[152:155], v[178:181], v[36:39]
	v_mfma_f32_16x16x32_bf16 v[28:31], v[160:163], v[178:181], v[28:31]
	v_mfma_f32_16x16x32_bf16 v[24:27], v[152:155], v[186:189], v[24:27]
	v_mfma_f32_16x16x32_bf16 v[20:23], v[160:163], v[186:189], v[20:23]
	v_mfma_f32_16x16x32_bf16 v[16:19], v[152:155], v[194:197], v[16:19]
	v_mfma_f32_16x16x32_bf16 v[12:15], v[160:163], v[194:197], v[12:15]
	v_mfma_f32_16x16x32_bf16 v[8:11], v[152:155], v[240:243], v[8:11]
	v_mfma_f32_16x16x32_bf16 v[2:5], v[160:163], v[240:243], v[4:7]
	v_mfma_f32_16x16x32_bf16 v[36:39], v[156:159], v[182:185], v[36:39]
	v_mfma_f32_16x16x32_bf16 v[28:31], v[174:177], v[182:185], v[28:31]
	v_mfma_f32_16x16x32_bf16 v[24:27], v[156:159], v[190:193], v[24:27]
	v_mfma_f32_16x16x32_bf16 v[20:23], v[174:177], v[190:193], v[20:23]
	v_mfma_f32_16x16x32_bf16 v[16:19], v[156:159], v[210:213], v[16:19]
	v_mfma_f32_16x16x32_bf16 v[12:15], v[174:177], v[210:213], v[12:15]
	v_mfma_f32_16x16x32_bf16 v[8:11], v[156:159], v[244:247], v[8:11]
	v_mfma_f32_16x16x32_bf16 v[2:5], v[174:177], v[244:247], v[2:5]
	s_barrier
	s_mov_b32 m0, s29
	s_nop 0
	global_load_lds_dwordx4 v164, s[54:55]
	s_mov_b32 m0, s45
	s_nop 0
	global_load_lds_dwordx4 v168, s[54:55]
	s_add_i32 s57, 0, 0x18000
	s_add_i32 s69, 0, 0x1c000
	ds_read_b128 v[136:139], v200 offset:32768
	ds_read_b128 v[140:143], v200 offset:33792
	ds_read_b128 v[144:147], v200 offset:34816
	ds_read_b128 v[148:151], v200 offset:35840
	ds_read_b128 v[152:155], v200 offset:49152
	ds_read_b128 v[156:159], v200 offset:50176
	ds_read_b128 v[160:163], v200 offset:51200
	ds_read_b128 v[174:177], v200 offset:52224
	s_add_u32 s34, s54, 0x80000
	s_addc_u32 s35, s55, 0
	s_mov_b32 m0, s82
	ds_read_b128 v[178:181], v199 offset:32768
	ds_read_b128 v[182:185], v199 offset:33792
	ds_read_b128 v[186:189], v199 offset:34816
	ds_read_b128 v[190:193], v199 offset:35840
	ds_read_b128 v[194:197], v199 offset:36864
	ds_read_b128 v[210:213], v199 offset:37888
	ds_read_b128 v[240:243], v199 offset:38912
	ds_read_b128 v[244:247], v199 offset:39936
	global_load_lds_dwordx4 v164, s[34:35]
	s_mov_b32 m0, s90
	s_nop 0
	global_load_lds_dwordx4 v168, s[34:35]
	s_waitcnt vmcnt(8) lgkmcnt(0)
	s_barrier
	v_mfma_f32_16x16x32_bf16 v[132:135], v[136:139], v[178:181], v[132:135]
	v_mfma_f32_16x16x32_bf16 v[128:131], v[144:147], v[178:181], v[128:131]
	v_mfma_f32_16x16x32_bf16 v[124:127], v[136:139], v[186:189], v[124:127]
	v_mfma_f32_16x16x32_bf16 v[120:123], v[144:147], v[186:189], v[120:123]
	v_mfma_f32_16x16x32_bf16 v[116:119], v[136:139], v[194:197], v[116:119]
	v_mfma_f32_16x16x32_bf16 v[112:115], v[144:147], v[194:197], v[112:115]
	v_mfma_f32_16x16x32_bf16 v[108:111], v[136:139], v[240:243], v[108:111]
	v_mfma_f32_16x16x32_bf16 v[104:107], v[144:147], v[240:243], v[104:107]
	v_mfma_f32_16x16x32_bf16 v[132:135], v[140:143], v[182:185], v[132:135]
	v_mfma_f32_16x16x32_bf16 v[128:131], v[148:151], v[182:185], v[128:131]
	v_mfma_f32_16x16x32_bf16 v[124:127], v[140:143], v[190:193], v[124:127]
	v_mfma_f32_16x16x32_bf16 v[120:123], v[148:151], v[190:193], v[120:123]
	v_mfma_f32_16x16x32_bf16 v[116:119], v[140:143], v[210:213], v[116:119]
	v_mfma_f32_16x16x32_bf16 v[112:115], v[148:151], v[210:213], v[112:115]
	v_mfma_f32_16x16x32_bf16 v[108:111], v[140:143], v[244:247], v[108:111]
	v_mfma_f32_16x16x32_bf16 v[104:107], v[148:151], v[244:247], v[104:107]
	v_mfma_f32_16x16x32_bf16 v[100:103], v[152:155], v[178:181], v[100:103]
	v_mfma_f32_16x16x32_bf16 v[96:99], v[160:163], v[178:181], v[96:99]
	v_mfma_f32_16x16x32_bf16 v[92:95], v[152:155], v[186:189], v[92:95]
	v_mfma_f32_16x16x32_bf16 v[88:91], v[160:163], v[186:189], v[88:91]
	v_mfma_f32_16x16x32_bf16 v[84:87], v[152:155], v[194:197], v[84:87]
	v_mfma_f32_16x16x32_bf16 v[80:83], v[160:163], v[194:197], v[80:83]
	v_mfma_f32_16x16x32_bf16 v[72:75], v[152:155], v[240:243], v[72:75]
	v_mfma_f32_16x16x32_bf16 v[64:67], v[160:163], v[240:243], v[64:67]
	v_mfma_f32_16x16x32_bf16 v[100:103], v[156:159], v[182:185], v[100:103]
	v_mfma_f32_16x16x32_bf16 v[96:99], v[174:177], v[182:185], v[96:99]
	v_mfma_f32_16x16x32_bf16 v[92:95], v[156:159], v[190:193], v[92:95]
	v_mfma_f32_16x16x32_bf16 v[88:91], v[174:177], v[190:193], v[88:91]
	v_mfma_f32_16x16x32_bf16 v[84:87], v[156:159], v[210:213], v[84:87]
	v_mfma_f32_16x16x32_bf16 v[80:83], v[174:177], v[210:213], v[80:83]
	v_mfma_f32_16x16x32_bf16 v[72:75], v[156:159], v[244:247], v[72:75]
	v_mfma_f32_16x16x32_bf16 v[64:67], v[174:177], v[244:247], v[64:67]
	s_barrier
	s_add_u32 s34, s52, 0x8000
	s_addc_u32 s35, s53, 0
	s_add_i32 s54, s57, s0
	s_mov_b32 m0, s54
	ds_read_b128 v[178:181], v199 offset:49152
	ds_read_b128 v[182:185], v199 offset:50176
	ds_read_b128 v[186:189], v199 offset:51200
	ds_read_b128 v[190:193], v199 offset:52224
	ds_read_b128 v[194:197], v199 offset:53248
	ds_read_b128 v[210:213], v199 offset:54272
	ds_read_b128 v[240:243], v199 offset:55296
	ds_read_b128 v[244:247], v199 offset:56320
	global_load_lds_dwordx4 v32, s[34:35]
	s_add_i32 m0, s54, 0x2000
	v_lshl_add_u64 v[6:7], s[34:35], 0, v[166:167]
	s_add_u32 s34, s52, 0xc000
	s_addc_u32 s35, s53, 0
	s_add_i32 s52, s69, s0
	global_load_lds_dwordx4 v[6:7], off
	s_mov_b32 m0, s52
	s_nop 0
	global_load_lds_dwordx4 v32, s[34:35]
	s_add_i32 m0, s52, 0x2000
	s_nop 0
	global_load_lds_dwordx4 v166, s[34:35]
	v_lshl_add_u64 v[6:7], v[248:249], 0, s[92:93]
	s_mov_b32 m0, s91
	s_nop 0
	global_load_lds_dwordx4 v[6:7], off
	v_lshl_add_u64 v[6:7], v[250:251], 0, s[92:93]
	s_mov_b32 m0, s30
	s_nop 0
	global_load_lds_dwordx4 v[6:7], off
	s_waitcnt vmcnt(8) lgkmcnt(0)
	s_barrier
	v_mfma_f32_16x16x32_bf16 v[76:79], v[136:139], v[178:181], v[76:79]
	v_mfma_f32_16x16x32_bf16 v[68:71], v[144:147], v[178:181], v[68:71]
	v_mfma_f32_16x16x32_bf16 v[60:63], v[136:139], v[186:189], v[60:63]
	v_mfma_f32_16x16x32_bf16 v[56:59], v[144:147], v[186:189], v[56:59]
	v_mfma_f32_16x16x32_bf16 v[52:55], v[136:139], v[194:197], v[52:55]
	v_mfma_f32_16x16x32_bf16 v[48:51], v[144:147], v[194:197], v[48:51]
	v_mfma_f32_16x16x32_bf16 v[44:47], v[136:139], v[240:243], v[44:47]
	v_mfma_f32_16x16x32_bf16 v[40:43], v[144:147], v[240:243], v[40:43]
	v_mfma_f32_16x16x32_bf16 v[76:79], v[140:143], v[182:185], v[76:79]
	v_mfma_f32_16x16x32_bf16 v[68:71], v[148:151], v[182:185], v[68:71]
	v_mfma_f32_16x16x32_bf16 v[60:63], v[140:143], v[190:193], v[60:63]
	v_mfma_f32_16x16x32_bf16 v[56:59], v[148:151], v[190:193], v[56:59]
	v_mfma_f32_16x16x32_bf16 v[52:55], v[140:143], v[210:213], v[52:55]
	v_mfma_f32_16x16x32_bf16 v[48:51], v[148:151], v[210:213], v[48:51]
	v_mfma_f32_16x16x32_bf16 v[44:47], v[140:143], v[244:247], v[44:47]
	v_mfma_f32_16x16x32_bf16 v[40:43], v[148:151], v[244:247], v[40:43]
	v_mfma_f32_16x16x32_bf16 v[36:39], v[152:155], v[178:181], v[36:39]
	v_mfma_f32_16x16x32_bf16 v[28:31], v[160:163], v[178:181], v[28:31]
	v_mfma_f32_16x16x32_bf16 v[24:27], v[152:155], v[186:189], v[24:27]
	v_mfma_f32_16x16x32_bf16 v[20:23], v[160:163], v[186:189], v[20:23]
	v_mfma_f32_16x16x32_bf16 v[16:19], v[152:155], v[194:197], v[16:19]
	v_mfma_f32_16x16x32_bf16 v[12:15], v[160:163], v[194:197], v[12:15]
	v_mfma_f32_16x16x32_bf16 v[6:9], v[152:155], v[240:243], v[8:11]
	v_mfma_f32_16x16x32_bf16 v[2:5], v[160:163], v[240:243], v[2:5]
	v_mfma_f32_16x16x32_bf16 v[36:39], v[156:159], v[182:185], v[36:39]
	v_mfma_f32_16x16x32_bf16 v[28:31], v[174:177], v[182:185], v[28:31]
	v_mfma_f32_16x16x32_bf16 v[24:27], v[156:159], v[190:193], v[24:27]
	v_mfma_f32_16x16x32_bf16 v[20:23], v[174:177], v[190:193], v[20:23]
	v_mfma_f32_16x16x32_bf16 v[16:19], v[156:159], v[210:213], v[16:19]
	v_mfma_f32_16x16x32_bf16 v[12:15], v[174:177], v[210:213], v[12:15]
	v_mfma_f32_16x16x32_bf16 v[8:11], v[156:159], v[244:247], v[6:9]
	v_mfma_f32_16x16x32_bf16 v[4:7], v[174:177], v[244:247], v[2:5]
	s_barrier
	s_add_i32 s56, s56, 2
	s_add_u32 s15, s15, 0x10000
	s_addc_u32 s51, s51, 0
	s_add_u32 s48, s48, 0x100
	s_addc_u32 s49, s49, 0
	s_cmp_gt_u32 s56, 29
	s_cbranch_scc0 .LBB0_788
	s_and_b64 vcc, exec, s[46:47]
	s_cbranch_vccz .LBB0_791
	s_barrier

.LBB0_877:
	s_add_u32 s62, s60, 0x100
	s_addc_u32 s63, s61, 0
	s_add_i32 s34, 0, 0x10000
	s_cmp_eq_u32 s49, 60
	s_cselect_b32 s67, s51, s63
	s_cselect_b32 s66, s50, s62
	s_cselect_b32 s65, s53, s28
	s_cselect_b32 s64, s52, s13
	s_add_i32 s55, 0, 0x14000
	ds_read_b128 v[132:135], v190 offset:0
	ds_read_b128 v[136:139], v190 offset:1024
	ds_read_b128 v[140:143], v190 offset:2048
	ds_read_b128 v[144:147], v190 offset:3072
	ds_read_b128 v[148:151], v190 offset:16384
	ds_read_b128 v[152:155], v190 offset:17408
	ds_read_b128 v[168:171], v190 offset:18432
	ds_read_b128 v[172:175], v190 offset:19456
	s_add_i32 m0, s29, 0xc000
	ds_read_b128 v[176:179], v189
	ds_read_b128 v[180:183], v189 offset:1024
	ds_read_b128 v[184:187], v189 offset:2048
	ds_read_b128 v[192:195], v189 offset:3072
	ds_read_b128 v[210:213], v189 offset:4096
	ds_read_b128 v[234:237], v189 offset:5120
	ds_read_b128 v[238:241], v189 offset:6144
	ds_read_b128 v[242:245], v189 offset:7168
	global_load_lds_dwordx4 v164, s[60:61]
	s_add_i32 m0, s29, 0xe000
	s_nop 0
	global_load_lds_dwordx4 v166, s[60:61]
	s_waitcnt vmcnt(8) lgkmcnt(0)
	s_barrier
	v_mfma_f32_16x16x32_bf16 v[128:131], v[132:135], v[176:179], v[128:131]
	v_mfma_f32_16x16x32_bf16 v[124:127], v[140:143], v[176:179], v[124:127]
	v_mfma_f32_16x16x32_bf16 v[112:115], v[132:135], v[184:187], v[112:115]
	v_mfma_f32_16x16x32_bf16 v[108:111], v[140:143], v[184:187], v[108:111]
	v_mfma_f32_16x16x32_bf16 v[96:99], v[132:135], v[210:213], v[96:99]
	v_mfma_f32_16x16x32_bf16 v[92:95], v[140:143], v[210:213], v[92:95]
	v_mfma_f32_16x16x32_bf16 v[80:83], v[132:135], v[238:241], v[80:83]
	v_mfma_f32_16x16x32_bf16 v[76:79], v[140:143], v[238:241], v[76:79]
	v_mfma_f32_16x16x32_bf16 v[128:131], v[136:139], v[180:183], v[128:131]
	v_mfma_f32_16x16x32_bf16 v[124:127], v[144:147], v[180:183], v[124:127]
	v_mfma_f32_16x16x32_bf16 v[112:115], v[136:139], v[192:195], v[112:115]
	v_mfma_f32_16x16x32_bf16 v[108:111], v[144:147], v[192:195], v[108:111]
	v_mfma_f32_16x16x32_bf16 v[96:99], v[136:139], v[234:237], v[96:99]
	v_mfma_f32_16x16x32_bf16 v[92:95], v[144:147], v[234:237], v[92:95]
	v_mfma_f32_16x16x32_bf16 v[80:83], v[136:139], v[242:245], v[80:83]
	v_mfma_f32_16x16x32_bf16 v[76:79], v[144:147], v[242:245], v[76:79]
	v_mfma_f32_16x16x32_bf16 v[120:123], v[148:151], v[176:179], v[120:123]
	v_mfma_f32_16x16x32_bf16 v[116:119], v[168:171], v[176:179], v[116:119]
	v_mfma_f32_16x16x32_bf16 v[104:107], v[148:151], v[184:187], v[104:107]
	v_mfma_f32_16x16x32_bf16 v[100:103], v[168:171], v[184:187], v[100:103]
	v_mfma_f32_16x16x32_bf16 v[88:91], v[148:151], v[210:213], v[88:91]
	v_mfma_f32_16x16x32_bf16 v[84:87], v[168:171], v[210:213], v[84:87]
	v_mfma_f32_16x16x32_bf16 v[72:75], v[148:151], v[238:241], v[72:75]
	v_mfma_f32_16x16x32_bf16 v[68:71], v[168:171], v[238:241], v[68:71]
	v_mfma_f32_16x16x32_bf16 v[120:123], v[152:155], v[180:183], v[120:123]
	v_mfma_f32_16x16x32_bf16 v[116:119], v[172:175], v[180:183], v[116:119]
	v_mfma_f32_16x16x32_bf16 v[104:107], v[152:155], v[192:195], v[104:107]
	v_mfma_f32_16x16x32_bf16 v[100:103], v[172:175], v[192:195], v[100:103]
	v_mfma_f32_16x16x32_bf16 v[88:91], v[152:155], v[234:237], v[88:91]
	v_mfma_f32_16x16x32_bf16 v[84:87], v[172:175], v[234:237], v[84:87]
	v_mfma_f32_16x16x32_bf16 v[72:75], v[152:155], v[242:245], v[72:75]
	v_mfma_f32_16x16x32_bf16 v[68:71], v[172:175], v[242:245], v[68:71]
	s_barrier
	s_add_i32 s34, s34, s0
	s_mov_b32 m0, s34
	ds_read_b128 v[176:179], v189 offset:16384
	ds_read_b128 v[180:183], v189 offset:17408
	ds_read_b128 v[184:187], v189 offset:18432
	ds_read_b128 v[192:195], v189 offset:19456
	ds_read_b128 v[210:213], v189 offset:20480
	ds_read_b128 v[234:237], v189 offset:21504
	ds_read_b128 v[238:241], v189 offset:22528
	ds_read_b128 v[242:245], v189 offset:23552
	global_load_lds_dwordx4 v156, s[64:65]
	s_add_i32 m0, s34, 0x2000
	s_add_u32 s34, s64, 0x4000
	s_addc_u32 s35, s65, 0
	s_add_i32 s55, s55, s0
	global_load_lds_dwordx4 v160, s[64:65]
	s_mov_b32 m0, s55
	s_nop 0
	global_load_lds_dwordx4 v156, s[34:35]
	s_add_i32 m0, s55, 0x2000
	s_nop 0
	global_load_lds_dwordx4 v160, s[34:35]
	s_waitcnt vmcnt(6) lgkmcnt(0)
	s_barrier
	v_mfma_f32_16x16x32_bf16 v[64:67], v[132:135], v[176:179], v[64:67]
	v_mfma_f32_16x16x32_bf16 v[60:63], v[140:143], v[176:179], v[60:63]
	v_mfma_f32_16x16x32_bf16 v[48:51], v[132:135], v[184:187], v[48:51]
	v_mfma_f32_16x16x32_bf16 v[44:47], v[140:143], v[184:187], v[44:47]
	v_mfma_f32_16x16x32_bf16 v[30:33], v[132:135], v[210:213], v[30:33]
	v_mfma_f32_16x16x32_bf16 v[26:29], v[140:143], v[210:213], v[26:29]
	v_mfma_f32_16x16x32_bf16 v[14:17], v[132:135], v[238:241], v[14:17]
	v_mfma_f32_16x16x32_bf16 v[10:13], v[140:143], v[238:241], v[10:13]
	v_mfma_f32_16x16x32_bf16 v[64:67], v[136:139], v[180:183], v[64:67]
	v_mfma_f32_16x16x32_bf16 v[60:63], v[144:147], v[180:183], v[60:63]
	v_mfma_f32_16x16x32_bf16 v[48:51], v[136:139], v[192:195], v[48:51]
	v_mfma_f32_16x16x32_bf16 v[44:47], v[144:147], v[192:195], v[44:47]
	v_mfma_f32_16x16x32_bf16 v[30:33], v[136:139], v[234:237], v[30:33]
	v_mfma_f32_16x16x32_bf16 v[26:29], v[144:147], v[234:237], v[26:29]
	v_mfma_f32_16x16x32_bf16 v[14:17], v[136:139], v[242:245], v[14:17]
	v_mfma_f32_16x16x32_bf16 v[10:13], v[144:147], v[242:245], v[10:13]
	v_mfma_f32_16x16x32_bf16 v[56:59], v[148:151], v[176:179], v[56:59]
	v_mfma_f32_16x16x32_bf16 v[52:55], v[168:171], v[176:179], v[52:55]
	v_mfma_f32_16x16x32_bf16 v[40:43], v[148:151], v[184:187], v[40:43]
	v_mfma_f32_16x16x32_bf16 v[36:39], v[168:171], v[184:187], v[36:39]
	v_mfma_f32_16x16x32_bf16 v[22:25], v[148:151], v[210:213], v[22:25]
	v_mfma_f32_16x16x32_bf16 v[18:21], v[168:171], v[210:213], v[18:21]
	v_mfma_f32_16x16x32_bf16 v[6:9], v[148:151], v[238:241], v[6:9]
	v_mfma_f32_16x16x32_bf16 v[2:5], v[168:171], v[238:241], v[2:5]
	v_mfma_f32_16x16x32_bf16 v[56:59], v[152:155], v[180:183], v[56:59]
	v_mfma_f32_16x16x32_bf16 v[52:55], v[172:175], v[180:183], v[52:55]
	v_mfma_f32_16x16x32_bf16 v[40:43], v[152:155], v[192:195], v[40:43]
	v_mfma_f32_16x16x32_bf16 v[36:39], v[172:175], v[192:195], v[36:39]
	v_mfma_f32_16x16x32_bf16 v[22:25], v[152:155], v[234:237], v[22:25]
	v_mfma_f32_16x16x32_bf16 v[18:21], v[172:175], v[234:237], v[18:21]
	v_mfma_f32_16x16x32_bf16 v[6:9], v[152:155], v[242:245], v[6:9]
	v_mfma_f32_16x16x32_bf16 v[2:5], v[172:175], v[242:245], v[2:5]
	s_barrier
	s_mov_b32 m0, s29
	s_nop 0
	global_load_lds_dwordx4 v158, s[66:67]
	s_mov_b32 m0, s45
	s_nop 0
	global_load_lds_dwordx4 v162, s[66:67]
	s_add_i32 s55, 0, 0x18000
	s_add_i32 s58, 0, 0x1c000
	ds_read_b128 v[132:135], v190 offset:32768
	ds_read_b128 v[136:139], v190 offset:33792
	ds_read_b128 v[140:143], v190 offset:34816
	ds_read_b128 v[144:147], v190 offset:35840
	ds_read_b128 v[148:151], v190 offset:49152
	ds_read_b128 v[152:155], v190 offset:50176
	ds_read_b128 v[168:171], v190 offset:51200
	ds_read_b128 v[172:175], v190 offset:52224
	s_add_u32 s34, s66, 0x100000
	s_addc_u32 s35, s67, 0
	s_mov_b32 m0, s82
	ds_read_b128 v[176:179], v189 offset:32768
	ds_read_b128 v[180:183], v189 offset:33792
	ds_read_b128 v[184:187], v189 offset:34816
	ds_read_b128 v[192:195], v189 offset:35840
	ds_read_b128 v[210:213], v189 offset:36864
	ds_read_b128 v[234:237], v189 offset:37888
	ds_read_b128 v[238:241], v189 offset:38912
	ds_read_b128 v[242:245], v189 offset:39936
	global_load_lds_dwordx4 v158, s[34:35]
	s_mov_b32 m0, s90
	s_nop 0
	global_load_lds_dwordx4 v162, s[34:35]
	s_waitcnt vmcnt(8) lgkmcnt(0)
	s_barrier
	v_mfma_f32_16x16x32_bf16 v[128:131], v[132:135], v[176:179], v[128:131]
	v_mfma_f32_16x16x32_bf16 v[124:127], v[140:143], v[176:179], v[124:127]
	v_mfma_f32_16x16x32_bf16 v[112:115], v[132:135], v[184:187], v[112:115]
	v_mfma_f32_16x16x32_bf16 v[108:111], v[140:143], v[184:187], v[108:111]
	v_mfma_f32_16x16x32_bf16 v[96:99], v[132:135], v[210:213], v[96:99]
	v_mfma_f32_16x16x32_bf16 v[92:95], v[140:143], v[210:213], v[92:95]
	v_mfma_f32_16x16x32_bf16 v[80:83], v[132:135], v[238:241], v[80:83]
	v_mfma_f32_16x16x32_bf16 v[76:79], v[140:143], v[238:241], v[76:79]
	v_mfma_f32_16x16x32_bf16 v[128:131], v[136:139], v[180:183], v[128:131]
	v_mfma_f32_16x16x32_bf16 v[124:127], v[144:147], v[180:183], v[124:127]
	v_mfma_f32_16x16x32_bf16 v[112:115], v[136:139], v[192:195], v[112:115]
	v_mfma_f32_16x16x32_bf16 v[108:111], v[144:147], v[192:195], v[108:111]
	v_mfma_f32_16x16x32_bf16 v[96:99], v[136:139], v[234:237], v[96:99]
	v_mfma_f32_16x16x32_bf16 v[92:95], v[144:147], v[234:237], v[92:95]
	v_mfma_f32_16x16x32_bf16 v[80:83], v[136:139], v[242:245], v[80:83]
	v_mfma_f32_16x16x32_bf16 v[76:79], v[144:147], v[242:245], v[76:79]
	v_mfma_f32_16x16x32_bf16 v[120:123], v[148:151], v[176:179], v[120:123]
	v_mfma_f32_16x16x32_bf16 v[116:119], v[168:171], v[176:179], v[116:119]
	v_mfma_f32_16x16x32_bf16 v[104:107], v[148:151], v[184:187], v[104:107]
	v_mfma_f32_16x16x32_bf16 v[100:103], v[168:171], v[184:187], v[100:103]
	v_mfma_f32_16x16x32_bf16 v[88:91], v[148:151], v[210:213], v[88:91]
	v_mfma_f32_16x16x32_bf16 v[84:87], v[168:171], v[210:213], v[84:87]
	v_mfma_f32_16x16x32_bf16 v[72:75], v[148:151], v[238:241], v[72:75]
	v_mfma_f32_16x16x32_bf16 v[68:71], v[168:171], v[238:241], v[68:71]
	v_mfma_f32_16x16x32_bf16 v[120:123], v[152:155], v[180:183], v[120:123]
	v_mfma_f32_16x16x32_bf16 v[116:119], v[172:175], v[180:183], v[116:119]
	v_mfma_f32_16x16x32_bf16 v[104:107], v[152:155], v[192:195], v[104:107]
	v_mfma_f32_16x16x32_bf16 v[100:103], v[172:175], v[192:195], v[100:103]
	v_mfma_f32_16x16x32_bf16 v[88:91], v[152:155], v[234:237], v[88:91]
	v_mfma_f32_16x16x32_bf16 v[84:87], v[172:175], v[234:237], v[84:87]
	v_mfma_f32_16x16x32_bf16 v[72:75], v[152:155], v[242:245], v[72:75]
	v_mfma_f32_16x16x32_bf16 v[68:71], v[172:175], v[242:245], v[68:71]
	s_barrier
	s_add_u32 s34, s64, 0x8000
	s_addc_u32 s35, s65, 0
	s_add_i32 s55, s55, s0
	s_mov_b32 m0, s55
	ds_read_b128 v[176:179], v189 offset:49152
	ds_read_b128 v[180:183], v189 offset:50176
	ds_read_b128 v[184:187], v189 offset:51200
	ds_read_b128 v[192:195], v189 offset:52224
	ds_read_b128 v[210:213], v189 offset:53248
	ds_read_b128 v[234:237], v189 offset:54272
	ds_read_b128 v[238:241], v189 offset:55296
	ds_read_b128 v[242:245], v189 offset:56320
	global_load_lds_dwordx4 v156, s[34:35]
	s_add_i32 m0, s55, 0x2000
	s_mov_b64 s[100:101], s[34:35]
	s_add_u32 s34, s64, 0xc000
	s_addc_u32 s35, s65, 0
	s_add_i32 s55, s58, s0
	global_load_lds_dwordx4 v160, s[100:101]
	s_mov_b32 m0, s55
	s_nop 0
	global_load_lds_dwordx4 v156, s[34:35]
	s_add_i32 m0, s55, 0x2000
	s_nop 0
	global_load_lds_dwordx4 v160, s[34:35]
	s_mov_b32 m0, s91
	s_nop 0
	s_add_u32 s100, s66, s92
	s_addc_u32 s101, s67, s93
	global_load_lds_dwordx4 v158, s[100:101]
	s_mov_b32 m0, s30
	s_nop 0
	s_add_u32 s100, s66, s92
	s_addc_u32 s101, s67, s93
	global_load_lds_dwordx4 v162, s[100:101]
	s_waitcnt vmcnt(8) lgkmcnt(0)
	s_barrier
	v_mfma_f32_16x16x32_bf16 v[64:67], v[132:135], v[176:179], v[64:67]
	v_mfma_f32_16x16x32_bf16 v[60:63], v[140:143], v[176:179], v[60:63]
	v_mfma_f32_16x16x32_bf16 v[48:51], v[132:135], v[184:187], v[48:51]
	v_mfma_f32_16x16x32_bf16 v[44:47], v[140:143], v[184:187], v[44:47]
	v_mfma_f32_16x16x32_bf16 v[30:33], v[132:135], v[210:213], v[30:33]
	v_mfma_f32_16x16x32_bf16 v[26:29], v[140:143], v[210:213], v[26:29]
	v_mfma_f32_16x16x32_bf16 v[14:17], v[132:135], v[238:241], v[14:17]
	v_mfma_f32_16x16x32_bf16 v[10:13], v[140:143], v[238:241], v[10:13]
	v_mfma_f32_16x16x32_bf16 v[64:67], v[136:139], v[180:183], v[64:67]
	v_mfma_f32_16x16x32_bf16 v[60:63], v[144:147], v[180:183], v[60:63]
	v_mfma_f32_16x16x32_bf16 v[48:51], v[136:139], v[192:195], v[48:51]
	v_mfma_f32_16x16x32_bf16 v[44:47], v[144:147], v[192:195], v[44:47]
	v_mfma_f32_16x16x32_bf16 v[30:33], v[136:139], v[234:237], v[30:33]
	v_mfma_f32_16x16x32_bf16 v[26:29], v[144:147], v[234:237], v[26:29]
	v_mfma_f32_16x16x32_bf16 v[14:17], v[136:139], v[242:245], v[14:17]
	v_mfma_f32_16x16x32_bf16 v[10:13], v[144:147], v[242:245], v[10:13]
	v_mfma_f32_16x16x32_bf16 v[56:59], v[148:151], v[176:179], v[56:59]
	v_mfma_f32_16x16x32_bf16 v[52:55], v[168:171], v[176:179], v[52:55]
	v_mfma_f32_16x16x32_bf16 v[40:43], v[148:151], v[184:187], v[40:43]
	v_mfma_f32_16x16x32_bf16 v[36:39], v[168:171], v[184:187], v[36:39]
	v_mfma_f32_16x16x32_bf16 v[22:25], v[148:151], v[210:213], v[22:25]
	v_mfma_f32_16x16x32_bf16 v[18:21], v[168:171], v[210:213], v[18:21]
	v_mfma_f32_16x16x32_bf16 v[6:9], v[148:151], v[238:241], v[6:9]
	v_mfma_f32_16x16x32_bf16 v[2:5], v[168:171], v[238:241], v[2:5]
	v_mfma_f32_16x16x32_bf16 v[56:59], v[152:155], v[180:183], v[56:59]
	v_mfma_f32_16x16x32_bf16 v[52:55], v[172:175], v[180:183], v[52:55]
	v_mfma_f32_16x16x32_bf16 v[40:43], v[152:155], v[192:195], v[40:43]
	v_mfma_f32_16x16x32_bf16 v[36:39], v[172:175], v[192:195], v[36:39]
	v_mfma_f32_16x16x32_bf16 v[22:25], v[152:155], v[234:237], v[22:25]
	v_mfma_f32_16x16x32_bf16 v[18:21], v[172:175], v[234:237], v[18:21]
	v_mfma_f32_16x16x32_bf16 v[6:9], v[152:155], v[242:245], v[6:9]
	v_mfma_f32_16x16x32_bf16 v[2:5], v[172:175], v[242:245], v[2:5]
	s_barrier
	s_add_i32 s49, s49, 2
	s_add_u32 s13, s13, 0x10000
	s_addc_u32 s28, s28, 0
	s_cmp_gt_u32 s49, 61
	s_mov_b64 s[60:61], s[62:63]
	s_cbranch_scc0 .LBB0_877
	s_and_b64 vcc, exec, s[46:47]
	s_cbranch_vccz .LBB0_880
	s_barrier

.LBB0_1070:
	s_add_u32 s34, s12, 0xfff00080
	s_addc_u32 s35, s13, -1
	s_add_i32 s48, 0, 0x10000
	s_cmp_eq_u32 s59, 28
	s_cselect_b32 s67, s61, s35
	s_cselect_b32 s66, s60, s34
	s_cselect_b32 s65, s63, s58
	s_cselect_b32 s64, s62, s28
	s_add_i32 s49, 0, 0x14000
	ds_read_b128 v[100:103], v2 offset:0
	ds_read_b128 v[112:115], v2 offset:1024
	ds_read_b128 v[172:175], v2 offset:2048
	ds_read_b128 v[188:191], v2 offset:3072
	ds_read_b128 v[192:195], v2 offset:16384
	ds_read_b128 v[200:203], v2 offset:17408
	ds_read_b128 v[204:207], v2 offset:18432
	ds_read_b128 v[210:213], v2 offset:19456
	s_add_i32 m0, s29, 0xc000
	ds_read_b128 v[216:219], v197
	ds_read_b128 v[220:223], v197 offset:1024
	ds_read_b128 v[224:227], v197 offset:2048
	ds_read_b128 v[228:231], v197 offset:3072
	ds_read_b128 v[232:235], v197 offset:4096
	ds_read_b128 v[236:239], v197 offset:5120
	ds_read_b128 v[240:243], v197 offset:6144
	ds_read_b128 v[244:247], v197 offset:7168
	global_load_lds_dwordx4 v184, s[12:13]
	s_add_i32 m0, s29, 0xe000
	s_nop 0
	global_load_lds_dwordx4 v186, s[12:13]
	s_waitcnt vmcnt(8) lgkmcnt(0)
	s_barrier
	v_mfma_i32_16x16x64_i8 v[168:171], v[100:103], v[216:219], v[168:171]
	v_mfma_i32_16x16x64_i8 v[160:163], v[172:175], v[216:219], v[160:163]
	v_mfma_i32_16x16x64_i8 v[152:155], v[100:103], v[224:227], v[152:155]
	v_mfma_i32_16x16x64_i8 v[144:147], v[172:175], v[224:227], v[144:147]
	v_mfma_i32_16x16x64_i8 v[136:139], v[100:103], v[232:235], v[136:139]
	v_mfma_i32_16x16x64_i8 v[128:131], v[172:175], v[232:235], v[128:131]
	v_mfma_i32_16x16x64_i8 v[120:123], v[100:103], v[240:243], v[120:123]
	v_mfma_i32_16x16x64_i8 v[108:111], v[172:175], v[240:243], v[108:111]
	v_mfma_i32_16x16x64_i8 v[168:171], v[112:115], v[220:223], v[168:171]
	v_mfma_i32_16x16x64_i8 v[160:163], v[188:191], v[220:223], v[160:163]
	v_mfma_i32_16x16x64_i8 v[152:155], v[112:115], v[228:231], v[152:155]
	v_mfma_i32_16x16x64_i8 v[144:147], v[188:191], v[228:231], v[144:147]
	v_mfma_i32_16x16x64_i8 v[136:139], v[112:115], v[236:239], v[136:139]
	v_mfma_i32_16x16x64_i8 v[128:131], v[188:191], v[236:239], v[128:131]
	v_mfma_i32_16x16x64_i8 v[120:123], v[112:115], v[244:247], v[120:123]
	v_mfma_i32_16x16x64_i8 v[108:111], v[188:191], v[244:247], v[108:111]
	v_mfma_i32_16x16x64_i8 v[164:167], v[192:195], v[216:219], v[164:167]
	v_mfma_i32_16x16x64_i8 v[156:159], v[204:207], v[216:219], v[156:159]
	v_mfma_i32_16x16x64_i8 v[148:151], v[192:195], v[224:227], v[148:151]
	v_mfma_i32_16x16x64_i8 v[140:143], v[204:207], v[224:227], v[140:143]
	v_mfma_i32_16x16x64_i8 v[132:135], v[192:195], v[232:235], v[132:135]
	v_mfma_i32_16x16x64_i8 v[124:127], v[204:207], v[232:235], v[124:127]
	v_mfma_i32_16x16x64_i8 v[116:119], v[192:195], v[240:243], v[116:119]
	v_mfma_i32_16x16x64_i8 v[104:107], v[204:207], v[240:243], v[104:107]
	v_mfma_i32_16x16x64_i8 v[164:167], v[200:203], v[220:223], v[164:167]
	v_mfma_i32_16x16x64_i8 v[156:159], v[210:213], v[220:223], v[156:159]
	v_mfma_i32_16x16x64_i8 v[148:151], v[200:203], v[228:231], v[148:151]
	v_mfma_i32_16x16x64_i8 v[140:143], v[210:213], v[228:231], v[140:143]
	v_mfma_i32_16x16x64_i8 v[132:135], v[200:203], v[236:239], v[132:135]
	v_mfma_i32_16x16x64_i8 v[124:127], v[210:213], v[236:239], v[124:127]
	v_mfma_i32_16x16x64_i8 v[116:119], v[200:203], v[244:247], v[116:119]
	v_mfma_i32_16x16x64_i8 v[104:107], v[210:213], v[244:247], v[104:107]
	s_barrier
	s_add_i32 s34, s48, s0
	s_mov_b32 m0, s34
	ds_read_b128 v[216:219], v197 offset:16384
	ds_read_b128 v[220:223], v197 offset:17408
	ds_read_b128 v[224:227], v197 offset:18432
	ds_read_b128 v[228:231], v197 offset:19456
	ds_read_b128 v[232:235], v197 offset:20480
	ds_read_b128 v[236:239], v197 offset:21504
	ds_read_b128 v[240:243], v197 offset:22528
	ds_read_b128 v[244:247], v197 offset:23552
	global_load_lds_dwordx4 v176, s[64:65]
	s_add_i32 m0, s34, 0x2000
	s_add_u32 s34, s64, 0x4000
	s_addc_u32 s35, s65, 0
	s_add_i32 s48, s49, s0
	global_load_lds_dwordx4 v180, s[64:65]
	s_mov_b32 m0, s48
	s_nop 0
	global_load_lds_dwordx4 v176, s[34:35]
	s_add_i32 m0, s48, 0x2000
	s_nop 0
	global_load_lds_dwordx4 v180, s[34:35]
	s_waitcnt vmcnt(6) lgkmcnt(0)
	s_barrier
	v_mfma_i32_16x16x64_i8 v[96:99], v[100:103], v[216:219], v[96:99]
	v_mfma_i32_16x16x64_i8 v[88:91], v[172:175], v[216:219], v[88:91]
	v_mfma_i32_16x16x64_i8 v[80:83], v[100:103], v[224:227], v[80:83]
	v_mfma_i32_16x16x64_i8 v[72:75], v[172:175], v[224:227], v[72:75]
	v_mfma_i32_16x16x64_i8 v[64:67], v[100:103], v[232:235], v[64:67]
	v_mfma_i32_16x16x64_i8 v[56:59], v[172:175], v[232:235], v[56:59]
	v_mfma_i32_16x16x64_i8 v[48:51], v[100:103], v[240:243], v[48:51]
	v_mfma_i32_16x16x64_i8 v[40:43], v[172:175], v[240:243], v[40:43]
	v_mfma_i32_16x16x64_i8 v[96:99], v[112:115], v[220:223], v[96:99]
	v_mfma_i32_16x16x64_i8 v[88:91], v[188:191], v[220:223], v[88:91]
	v_mfma_i32_16x16x64_i8 v[80:83], v[112:115], v[228:231], v[80:83]
	v_mfma_i32_16x16x64_i8 v[72:75], v[188:191], v[228:231], v[72:75]
	v_mfma_i32_16x16x64_i8 v[64:67], v[112:115], v[236:239], v[64:67]
	v_mfma_i32_16x16x64_i8 v[56:59], v[188:191], v[236:239], v[56:59]
	v_mfma_i32_16x16x64_i8 v[48:51], v[112:115], v[244:247], v[48:51]
	v_mfma_i32_16x16x64_i8 v[40:43], v[188:191], v[244:247], v[40:43]
	v_mfma_i32_16x16x64_i8 v[92:95], v[192:195], v[216:219], v[92:95]
	v_mfma_i32_16x16x64_i8 v[84:87], v[204:207], v[216:219], v[84:87]
	v_mfma_i32_16x16x64_i8 v[76:79], v[192:195], v[224:227], v[76:79]
	v_mfma_i32_16x16x64_i8 v[68:71], v[204:207], v[224:227], v[68:71]
	v_mfma_i32_16x16x64_i8 v[60:63], v[192:195], v[232:235], v[60:63]
	v_mfma_i32_16x16x64_i8 v[52:55], v[204:207], v[232:235], v[52:55]
	v_mfma_i32_16x16x64_i8 v[44:47], v[192:195], v[240:243], v[44:47]
	v_mfma_i32_16x16x64_i8 v[36:39], v[204:207], v[240:243], v[36:39]
	v_mfma_i32_16x16x64_i8 v[92:95], v[200:203], v[220:223], v[92:95]
	v_mfma_i32_16x16x64_i8 v[84:87], v[210:213], v[220:223], v[84:87]
	v_mfma_i32_16x16x64_i8 v[76:79], v[200:203], v[228:231], v[76:79]
	v_mfma_i32_16x16x64_i8 v[68:71], v[210:213], v[228:231], v[68:71]
	v_mfma_i32_16x16x64_i8 v[60:63], v[200:203], v[236:239], v[60:63]
	v_mfma_i32_16x16x64_i8 v[52:55], v[210:213], v[236:239], v[52:55]
	v_mfma_i32_16x16x64_i8 v[44:47], v[200:203], v[244:247], v[44:47]
	v_mfma_i32_16x16x64_i8 v[36:39], v[210:213], v[244:247], v[36:39]
	s_barrier
	s_mov_b32 m0, s29
	s_nop 0
	global_load_lds_dwordx4 v178, s[66:67]
	s_mov_b32 m0, s45
	s_nop 0
	global_load_lds_dwordx4 v182, s[66:67]
	s_add_i32 s48, 0, 0x18000
	s_add_i32 s49, 0, 0x1c000
	ds_read_b128 v[100:103], v2 offset:32768
	ds_read_b128 v[112:115], v2 offset:33792
	ds_read_b128 v[172:175], v2 offset:34816
	ds_read_b128 v[188:191], v2 offset:35840
	ds_read_b128 v[192:195], v2 offset:49152
	ds_read_b128 v[200:203], v2 offset:50176
	ds_read_b128 v[204:207], v2 offset:51200
	ds_read_b128 v[210:213], v2 offset:52224
	s_add_u32 s34, s66, 0x100000
	s_addc_u32 s35, s67, 0
	s_mov_b32 m0, s82
	ds_read_b128 v[216:219], v197 offset:32768
	ds_read_b128 v[220:223], v197 offset:33792
	ds_read_b128 v[224:227], v197 offset:34816
	ds_read_b128 v[228:231], v197 offset:35840
	ds_read_b128 v[232:235], v197 offset:36864
	ds_read_b128 v[236:239], v197 offset:37888
	ds_read_b128 v[240:243], v197 offset:38912
	ds_read_b128 v[244:247], v197 offset:39936
	global_load_lds_dwordx4 v178, s[34:35]
	s_mov_b32 m0, s90
	s_nop 0
	global_load_lds_dwordx4 v182, s[34:35]
	s_waitcnt vmcnt(8) lgkmcnt(0)
	s_barrier
	v_mfma_i32_16x16x64_i8 v[168:171], v[100:103], v[216:219], v[168:171]
	v_mfma_i32_16x16x64_i8 v[160:163], v[172:175], v[216:219], v[160:163]
	v_mfma_i32_16x16x64_i8 v[152:155], v[100:103], v[224:227], v[152:155]
	v_mfma_i32_16x16x64_i8 v[144:147], v[172:175], v[224:227], v[144:147]
	v_mfma_i32_16x16x64_i8 v[136:139], v[100:103], v[232:235], v[136:139]
	v_mfma_i32_16x16x64_i8 v[128:131], v[172:175], v[232:235], v[128:131]
	v_mfma_i32_16x16x64_i8 v[120:123], v[100:103], v[240:243], v[120:123]
	v_mfma_i32_16x16x64_i8 v[108:111], v[172:175], v[240:243], v[108:111]
	v_mfma_i32_16x16x64_i8 v[168:171], v[112:115], v[220:223], v[168:171]
	v_mfma_i32_16x16x64_i8 v[160:163], v[188:191], v[220:223], v[160:163]
	v_mfma_i32_16x16x64_i8 v[152:155], v[112:115], v[228:231], v[152:155]
	v_mfma_i32_16x16x64_i8 v[144:147], v[188:191], v[228:231], v[144:147]
	v_mfma_i32_16x16x64_i8 v[136:139], v[112:115], v[236:239], v[136:139]
	v_mfma_i32_16x16x64_i8 v[128:131], v[188:191], v[236:239], v[128:131]
	v_mfma_i32_16x16x64_i8 v[120:123], v[112:115], v[244:247], v[120:123]
	v_mfma_i32_16x16x64_i8 v[108:111], v[188:191], v[244:247], v[108:111]
	v_mfma_i32_16x16x64_i8 v[164:167], v[192:195], v[216:219], v[164:167]
	v_mfma_i32_16x16x64_i8 v[156:159], v[204:207], v[216:219], v[156:159]
	v_mfma_i32_16x16x64_i8 v[148:151], v[192:195], v[224:227], v[148:151]
	v_mfma_i32_16x16x64_i8 v[140:143], v[204:207], v[224:227], v[140:143]
	v_mfma_i32_16x16x64_i8 v[132:135], v[192:195], v[232:235], v[132:135]
	v_mfma_i32_16x16x64_i8 v[124:127], v[204:207], v[232:235], v[124:127]
	v_mfma_i32_16x16x64_i8 v[116:119], v[192:195], v[240:243], v[116:119]
	v_mfma_i32_16x16x64_i8 v[104:107], v[204:207], v[240:243], v[104:107]
	v_mfma_i32_16x16x64_i8 v[164:167], v[200:203], v[220:223], v[164:167]
	v_mfma_i32_16x16x64_i8 v[156:159], v[210:213], v[220:223], v[156:159]
	v_mfma_i32_16x16x64_i8 v[148:151], v[200:203], v[228:231], v[148:151]
	v_mfma_i32_16x16x64_i8 v[140:143], v[210:213], v[228:231], v[140:143]
	v_mfma_i32_16x16x64_i8 v[132:135], v[200:203], v[236:239], v[132:135]
	v_mfma_i32_16x16x64_i8 v[124:127], v[210:213], v[236:239], v[124:127]
	v_mfma_i32_16x16x64_i8 v[116:119], v[200:203], v[244:247], v[116:119]
	v_mfma_i32_16x16x64_i8 v[104:107], v[210:213], v[244:247], v[104:107]
	s_barrier
	s_add_u32 s34, s64, 0x8000
	s_addc_u32 s35, s65, 0
	s_add_i32 s48, s48, s0
	s_mov_b32 m0, s48
	ds_read_b128 v[216:219], v197 offset:49152
	ds_read_b128 v[220:223], v197 offset:50176
	ds_read_b128 v[224:227], v197 offset:51200
	ds_read_b128 v[228:231], v197 offset:52224
	ds_read_b128 v[232:235], v197 offset:53248
	ds_read_b128 v[236:239], v197 offset:54272
	ds_read_b128 v[240:243], v197 offset:55296
	ds_read_b128 v[244:247], v197 offset:56320
	global_load_lds_dwordx4 v176, s[34:35]
	s_add_i32 m0, s48, 0x2000
	s_mov_b64 s[100:101], s[34:35]
	s_add_u32 s34, s64, 0xc000
	s_addc_u32 s35, s65, 0
	s_add_i32 s48, s49, s0
	global_load_lds_dwordx4 v180, s[100:101]
	s_mov_b32 m0, s48
	s_nop 0
	global_load_lds_dwordx4 v176, s[34:35]
	s_add_i32 m0, s48, 0x2000
	s_nop 0
	global_load_lds_dwordx4 v180, s[34:35]
	s_mov_b32 m0, s91
	s_nop 0
	s_add_u32 s100, s66, s92
	s_addc_u32 s101, s67, s93
	global_load_lds_dwordx4 v178, s[100:101]
	s_mov_b32 m0, s30
	s_nop 0
	s_add_u32 s100, s66, s92
	s_addc_u32 s101, s67, s93
	global_load_lds_dwordx4 v182, s[100:101]
	s_waitcnt vmcnt(8) lgkmcnt(0)
	s_barrier
	v_mfma_i32_16x16x64_i8 v[96:99], v[100:103], v[216:219], v[96:99]
	v_mfma_i32_16x16x64_i8 v[88:91], v[172:175], v[216:219], v[88:91]
	v_mfma_i32_16x16x64_i8 v[80:83], v[100:103], v[224:227], v[80:83]
	v_mfma_i32_16x16x64_i8 v[72:75], v[172:175], v[224:227], v[72:75]
	v_mfma_i32_16x16x64_i8 v[64:67], v[100:103], v[232:235], v[64:67]
	v_mfma_i32_16x16x64_i8 v[56:59], v[172:175], v[232:235], v[56:59]
	v_mfma_i32_16x16x64_i8 v[48:51], v[100:103], v[240:243], v[48:51]
	v_mfma_i32_16x16x64_i8 v[40:43], v[172:175], v[240:243], v[40:43]
	v_mfma_i32_16x16x64_i8 v[96:99], v[112:115], v[220:223], v[96:99]
	v_mfma_i32_16x16x64_i8 v[88:91], v[188:191], v[220:223], v[88:91]
	v_mfma_i32_16x16x64_i8 v[80:83], v[112:115], v[228:231], v[80:83]
	v_mfma_i32_16x16x64_i8 v[72:75], v[188:191], v[228:231], v[72:75]
	v_mfma_i32_16x16x64_i8 v[64:67], v[112:115], v[236:239], v[64:67]
	v_mfma_i32_16x16x64_i8 v[56:59], v[188:191], v[236:239], v[56:59]
	v_mfma_i32_16x16x64_i8 v[48:51], v[112:115], v[244:247], v[48:51]
	v_mfma_i32_16x16x64_i8 v[40:43], v[188:191], v[244:247], v[40:43]
	v_mfma_i32_16x16x64_i8 v[92:95], v[192:195], v[216:219], v[92:95]
	v_mfma_i32_16x16x64_i8 v[84:87], v[204:207], v[216:219], v[84:87]
	v_mfma_i32_16x16x64_i8 v[76:79], v[192:195], v[224:227], v[76:79]
	v_mfma_i32_16x16x64_i8 v[68:71], v[204:207], v[224:227], v[68:71]
	v_mfma_i32_16x16x64_i8 v[60:63], v[192:195], v[232:235], v[60:63]
	v_mfma_i32_16x16x64_i8 v[52:55], v[204:207], v[232:235], v[52:55]
	v_mfma_i32_16x16x64_i8 v[44:47], v[192:195], v[240:243], v[44:47]
	v_mfma_i32_16x16x64_i8 v[36:39], v[204:207], v[240:243], v[36:39]
	v_mfma_i32_16x16x64_i8 v[92:95], v[200:203], v[220:223], v[92:95]
	v_mfma_i32_16x16x64_i8 v[84:87], v[210:213], v[220:223], v[84:87]
	v_mfma_i32_16x16x64_i8 v[76:79], v[200:203], v[228:231], v[76:79]
	v_mfma_i32_16x16x64_i8 v[68:71], v[210:213], v[228:231], v[68:71]
	v_mfma_i32_16x16x64_i8 v[60:63], v[200:203], v[236:239], v[60:63]
	v_mfma_i32_16x16x64_i8 v[52:55], v[210:213], v[236:239], v[52:55]
	v_mfma_i32_16x16x64_i8 v[44:47], v[200:203], v[244:247], v[44:47]
	v_mfma_i32_16x16x64_i8 v[36:39], v[210:213], v[244:247], v[36:39]
	s_barrier
	s_add_i32 s59, s59, 2
	s_add_u32 s28, s28, 0x10000
	s_addc_u32 s58, s58, 0
	s_add_u32 s12, s12, 0x100
	s_addc_u32 s13, s13, 0
	s_cmp_gt_u32 s59, 29
	s_cbranch_scc0 .LBB0_1070
	s_and_b64 vcc, exec, s[46:47]
	s_cbranch_vccz .LBB0_1073
	s_barrier

.LBB0_1261:
	s_add_u32 s42, s22, 0x100
	s_addc_u32 s43, s23, 0
	s_add_i32 s34, 0, 0x10000
	s_cmpk_eq_i32 s60, 0xa8
	s_cselect_b32 s51, s19, s43
	s_cselect_b32 s50, s18, s42
	s_cselect_b32 s49, s21, s59
	s_cselect_b32 s48, s20, s58
	s_add_i32 s35, 0, 0x14000
	ds_read_b128 v[132:135], v188 offset:0
	ds_read_b128 v[136:139], v188 offset:1024
	ds_read_b128 v[140:143], v188 offset:2048
	ds_read_b128 v[144:147], v188 offset:3072
	ds_read_b128 v[148:151], v188 offset:16384
	ds_read_b128 v[152:155], v188 offset:17408
	ds_read_b128 v[168:171], v188 offset:18432
	ds_read_b128 v[172:175], v188 offset:19456
	s_add_i32 m0, s29, 0xc000
	ds_read_b128 v[176:179], v187
	ds_read_b128 v[180:183], v187 offset:1024
	ds_read_b128 v[192:195], v187 offset:2048
	ds_read_b128 v[210:213], v187 offset:3072
	ds_read_b128 v[232:235], v187 offset:4096
	ds_read_b128 v[236:239], v187 offset:5120
	ds_read_b128 v[240:243], v187 offset:6144
	ds_read_b128 v[244:247], v187 offset:7168
	global_load_lds_dwordx4 v164, s[22:23]
	s_add_i32 m0, s29, 0xe000
	s_nop 0
	global_load_lds_dwordx4 v166, s[22:23]
	s_waitcnt vmcnt(8) lgkmcnt(0)
	s_barrier
	v_mfma_f32_16x16x32_bf16 v[128:131], v[132:135], v[176:179], v[128:131]
	v_mfma_f32_16x16x32_bf16 v[124:127], v[140:143], v[176:179], v[124:127]
	v_mfma_f32_16x16x32_bf16 v[112:115], v[132:135], v[192:195], v[112:115]
	v_mfma_f32_16x16x32_bf16 v[108:111], v[140:143], v[192:195], v[108:111]
	v_mfma_f32_16x16x32_bf16 v[96:99], v[132:135], v[232:235], v[96:99]
	v_mfma_f32_16x16x32_bf16 v[92:95], v[140:143], v[232:235], v[92:95]
	v_mfma_f32_16x16x32_bf16 v[80:83], v[132:135], v[240:243], v[80:83]
	v_mfma_f32_16x16x32_bf16 v[76:79], v[140:143], v[240:243], v[76:79]
	v_mfma_f32_16x16x32_bf16 v[128:131], v[136:139], v[180:183], v[128:131]
	v_mfma_f32_16x16x32_bf16 v[124:127], v[144:147], v[180:183], v[124:127]
	v_mfma_f32_16x16x32_bf16 v[112:115], v[136:139], v[210:213], v[112:115]
	v_mfma_f32_16x16x32_bf16 v[108:111], v[144:147], v[210:213], v[108:111]
	v_mfma_f32_16x16x32_bf16 v[96:99], v[136:139], v[236:239], v[96:99]
	v_mfma_f32_16x16x32_bf16 v[92:95], v[144:147], v[236:239], v[92:95]
	v_mfma_f32_16x16x32_bf16 v[80:83], v[136:139], v[244:247], v[80:83]
	v_mfma_f32_16x16x32_bf16 v[76:79], v[144:147], v[244:247], v[76:79]
	v_mfma_f32_16x16x32_bf16 v[120:123], v[148:151], v[176:179], v[120:123]
	v_mfma_f32_16x16x32_bf16 v[116:119], v[168:171], v[176:179], v[116:119]
	v_mfma_f32_16x16x32_bf16 v[104:107], v[148:151], v[192:195], v[104:107]
	v_mfma_f32_16x16x32_bf16 v[100:103], v[168:171], v[192:195], v[100:103]
	v_mfma_f32_16x16x32_bf16 v[88:91], v[148:151], v[232:235], v[88:91]
	v_mfma_f32_16x16x32_bf16 v[84:87], v[168:171], v[232:235], v[84:87]
	v_mfma_f32_16x16x32_bf16 v[72:75], v[148:151], v[240:243], v[72:75]
	v_mfma_f32_16x16x32_bf16 v[68:71], v[168:171], v[240:243], v[68:71]
	v_mfma_f32_16x16x32_bf16 v[120:123], v[152:155], v[180:183], v[120:123]
	v_mfma_f32_16x16x32_bf16 v[116:119], v[172:175], v[180:183], v[116:119]
	v_mfma_f32_16x16x32_bf16 v[104:107], v[152:155], v[210:213], v[104:107]
	v_mfma_f32_16x16x32_bf16 v[100:103], v[172:175], v[210:213], v[100:103]
	v_mfma_f32_16x16x32_bf16 v[88:91], v[152:155], v[236:239], v[88:91]
	v_mfma_f32_16x16x32_bf16 v[84:87], v[172:175], v[236:239], v[84:87]
	v_mfma_f32_16x16x32_bf16 v[72:75], v[152:155], v[244:247], v[72:75]
	v_mfma_f32_16x16x32_bf16 v[68:71], v[172:175], v[244:247], v[68:71]
	s_barrier
	s_add_i32 s22, s34, s0
	s_mov_b32 m0, s22
	ds_read_b128 v[176:179], v187 offset:16384
	ds_read_b128 v[180:183], v187 offset:17408
	ds_read_b128 v[192:195], v187 offset:18432
	ds_read_b128 v[210:213], v187 offset:19456
	ds_read_b128 v[232:235], v187 offset:20480
	ds_read_b128 v[236:239], v187 offset:21504
	ds_read_b128 v[240:243], v187 offset:22528
	ds_read_b128 v[244:247], v187 offset:23552
	global_load_lds_dwordx4 v156, s[48:49]
	s_add_i32 m0, s22, 0x2000
	s_add_u32 s22, s48, 0x4000
	s_addc_u32 s23, s49, 0
	s_add_i32 s34, s35, s0
	global_load_lds_dwordx4 v160, s[48:49]
	s_mov_b32 m0, s34
	s_nop 0
	global_load_lds_dwordx4 v156, s[22:23]
	s_add_i32 m0, s34, 0x2000
	s_nop 0
	global_load_lds_dwordx4 v160, s[22:23]
	s_waitcnt vmcnt(6) lgkmcnt(0)
	s_barrier
	v_mfma_f32_16x16x32_bf16 v[64:67], v[132:135], v[176:179], v[64:67]
	v_mfma_f32_16x16x32_bf16 v[60:63], v[140:143], v[176:179], v[60:63]
	v_mfma_f32_16x16x32_bf16 v[48:51], v[132:135], v[192:195], v[48:51]
	v_mfma_f32_16x16x32_bf16 v[44:47], v[140:143], v[192:195], v[44:47]
	v_mfma_f32_16x16x32_bf16 v[30:33], v[132:135], v[232:235], v[30:33]
	v_mfma_f32_16x16x32_bf16 v[26:29], v[140:143], v[232:235], v[26:29]
	v_mfma_f32_16x16x32_bf16 v[14:17], v[132:135], v[240:243], v[14:17]
	v_mfma_f32_16x16x32_bf16 v[10:13], v[140:143], v[240:243], v[10:13]
	v_mfma_f32_16x16x32_bf16 v[64:67], v[136:139], v[180:183], v[64:67]
	v_mfma_f32_16x16x32_bf16 v[60:63], v[144:147], v[180:183], v[60:63]
	v_mfma_f32_16x16x32_bf16 v[48:51], v[136:139], v[210:213], v[48:51]
	v_mfma_f32_16x16x32_bf16 v[44:47], v[144:147], v[210:213], v[44:47]
	v_mfma_f32_16x16x32_bf16 v[30:33], v[136:139], v[236:239], v[30:33]
	v_mfma_f32_16x16x32_bf16 v[26:29], v[144:147], v[236:239], v[26:29]
	v_mfma_f32_16x16x32_bf16 v[14:17], v[136:139], v[244:247], v[14:17]
	v_mfma_f32_16x16x32_bf16 v[10:13], v[144:147], v[244:247], v[10:13]
	v_mfma_f32_16x16x32_bf16 v[56:59], v[148:151], v[176:179], v[56:59]
	v_mfma_f32_16x16x32_bf16 v[52:55], v[168:171], v[176:179], v[52:55]
	v_mfma_f32_16x16x32_bf16 v[40:43], v[148:151], v[192:195], v[40:43]
	v_mfma_f32_16x16x32_bf16 v[36:39], v[168:171], v[192:195], v[36:39]
	v_mfma_f32_16x16x32_bf16 v[22:25], v[148:151], v[232:235], v[22:25]
	v_mfma_f32_16x16x32_bf16 v[18:21], v[168:171], v[232:235], v[18:21]
	v_mfma_f32_16x16x32_bf16 v[6:9], v[148:151], v[240:243], v[6:9]
	v_mfma_f32_16x16x32_bf16 v[2:5], v[168:171], v[240:243], v[2:5]
	v_mfma_f32_16x16x32_bf16 v[56:59], v[152:155], v[180:183], v[56:59]
	v_mfma_f32_16x16x32_bf16 v[52:55], v[172:175], v[180:183], v[52:55]
	v_mfma_f32_16x16x32_bf16 v[40:43], v[152:155], v[210:213], v[40:43]
	v_mfma_f32_16x16x32_bf16 v[36:39], v[172:175], v[210:213], v[36:39]
	v_mfma_f32_16x16x32_bf16 v[22:25], v[152:155], v[236:239], v[22:25]
	v_mfma_f32_16x16x32_bf16 v[18:21], v[172:175], v[236:239], v[18:21]
	v_mfma_f32_16x16x32_bf16 v[6:9], v[152:155], v[244:247], v[6:9]
	v_mfma_f32_16x16x32_bf16 v[2:5], v[172:175], v[244:247], v[2:5]
	s_barrier
	s_mov_b32 m0, s29
	s_nop 0
	global_load_lds_dwordx4 v158, s[50:51]
	s_mov_b32 m0, s45
	s_nop 0
	global_load_lds_dwordx4 v162, s[50:51]
	s_add_i32 s34, 0, 0x18000
	s_add_i32 s35, 0, 0x1c000
	ds_read_b128 v[132:135], v188 offset:32768
	ds_read_b128 v[136:139], v188 offset:33792
	ds_read_b128 v[140:143], v188 offset:34816
	ds_read_b128 v[144:147], v188 offset:35840
	ds_read_b128 v[148:151], v188 offset:49152
	ds_read_b128 v[152:155], v188 offset:50176
	ds_read_b128 v[168:171], v188 offset:51200
	ds_read_b128 v[172:175], v188 offset:52224
	s_add_u32 s22, s50, 0x2b0000
	s_addc_u32 s23, s51, 0
	s_mov_b32 m0, s82
	ds_read_b128 v[176:179], v187 offset:32768
	ds_read_b128 v[180:183], v187 offset:33792
	ds_read_b128 v[192:195], v187 offset:34816
	ds_read_b128 v[210:213], v187 offset:35840
	ds_read_b128 v[232:235], v187 offset:36864
	ds_read_b128 v[236:239], v187 offset:37888
	ds_read_b128 v[240:243], v187 offset:38912
	ds_read_b128 v[244:247], v187 offset:39936
	global_load_lds_dwordx4 v158, s[22:23]
	s_mov_b32 m0, s90
	s_nop 0
	global_load_lds_dwordx4 v162, s[22:23]
	s_waitcnt vmcnt(8) lgkmcnt(0)
	s_barrier
	v_mfma_f32_16x16x32_bf16 v[128:131], v[132:135], v[176:179], v[128:131]
	v_mfma_f32_16x16x32_bf16 v[124:127], v[140:143], v[176:179], v[124:127]
	v_mfma_f32_16x16x32_bf16 v[112:115], v[132:135], v[192:195], v[112:115]
	v_mfma_f32_16x16x32_bf16 v[108:111], v[140:143], v[192:195], v[108:111]
	v_mfma_f32_16x16x32_bf16 v[96:99], v[132:135], v[232:235], v[96:99]
	v_mfma_f32_16x16x32_bf16 v[92:95], v[140:143], v[232:235], v[92:95]
	v_mfma_f32_16x16x32_bf16 v[80:83], v[132:135], v[240:243], v[80:83]
	v_mfma_f32_16x16x32_bf16 v[76:79], v[140:143], v[240:243], v[76:79]
	v_mfma_f32_16x16x32_bf16 v[128:131], v[136:139], v[180:183], v[128:131]
	v_mfma_f32_16x16x32_bf16 v[124:127], v[144:147], v[180:183], v[124:127]
	v_mfma_f32_16x16x32_bf16 v[112:115], v[136:139], v[210:213], v[112:115]
	v_mfma_f32_16x16x32_bf16 v[108:111], v[144:147], v[210:213], v[108:111]
	v_mfma_f32_16x16x32_bf16 v[96:99], v[136:139], v[236:239], v[96:99]
	v_mfma_f32_16x16x32_bf16 v[92:95], v[144:147], v[236:239], v[92:95]
	v_mfma_f32_16x16x32_bf16 v[80:83], v[136:139], v[244:247], v[80:83]
	v_mfma_f32_16x16x32_bf16 v[76:79], v[144:147], v[244:247], v[76:79]
	v_mfma_f32_16x16x32_bf16 v[120:123], v[148:151], v[176:179], v[120:123]
	v_mfma_f32_16x16x32_bf16 v[116:119], v[168:171], v[176:179], v[116:119]
	v_mfma_f32_16x16x32_bf16 v[104:107], v[148:151], v[192:195], v[104:107]
	v_mfma_f32_16x16x32_bf16 v[100:103], v[168:171], v[192:195], v[100:103]
	v_mfma_f32_16x16x32_bf16 v[88:91], v[148:151], v[232:235], v[88:91]
	v_mfma_f32_16x16x32_bf16 v[84:87], v[168:171], v[232:235], v[84:87]
	v_mfma_f32_16x16x32_bf16 v[72:75], v[148:151], v[240:243], v[72:75]
	v_mfma_f32_16x16x32_bf16 v[68:71], v[168:171], v[240:243], v[68:71]
	v_mfma_f32_16x16x32_bf16 v[120:123], v[152:155], v[180:183], v[120:123]
	v_mfma_f32_16x16x32_bf16 v[116:119], v[172:175], v[180:183], v[116:119]
	v_mfma_f32_16x16x32_bf16 v[104:107], v[152:155], v[210:213], v[104:107]
	v_mfma_f32_16x16x32_bf16 v[100:103], v[172:175], v[210:213], v[100:103]
	v_mfma_f32_16x16x32_bf16 v[88:91], v[152:155], v[236:239], v[88:91]
	v_mfma_f32_16x16x32_bf16 v[84:87], v[172:175], v[236:239], v[84:87]
	v_mfma_f32_16x16x32_bf16 v[72:75], v[152:155], v[244:247], v[72:75]
	v_mfma_f32_16x16x32_bf16 v[68:71], v[172:175], v[244:247], v[68:71]
	s_barrier
	s_add_u32 s22, s48, 0x8000
	s_addc_u32 s23, s49, 0
	s_add_i32 s34, s34, s0
	s_mov_b32 m0, s34
	ds_read_b128 v[176:179], v187 offset:49152
	ds_read_b128 v[180:183], v187 offset:50176
	ds_read_b128 v[192:195], v187 offset:51200
	ds_read_b128 v[210:213], v187 offset:52224
	ds_read_b128 v[232:235], v187 offset:53248
	ds_read_b128 v[236:239], v187 offset:54272
	ds_read_b128 v[240:243], v187 offset:55296
	ds_read_b128 v[244:247], v187 offset:56320
	global_load_lds_dwordx4 v156, s[22:23]
	s_add_i32 m0, s34, 0x2000
	s_mov_b64 s[100:101], s[22:23]
	s_add_u32 s22, s48, 0xc000
	s_addc_u32 s23, s49, 0
	s_add_i32 s34, s35, s0
	global_load_lds_dwordx4 v160, s[100:101]
	s_mov_b32 m0, s34
	s_nop 0
	global_load_lds_dwordx4 v156, s[22:23]
	s_add_i32 m0, s34, 0x2000
	s_nop 0
	global_load_lds_dwordx4 v160, s[22:23]
	s_mov_b32 m0, s91
	s_nop 0
	s_add_u32 s100, s50, s92
	s_addc_u32 s101, s51, s93
	global_load_lds_dwordx4 v158, s[100:101]
	s_mov_b32 m0, s30
	s_nop 0
	s_add_u32 s100, s50, s92
	s_addc_u32 s101, s51, s93
	global_load_lds_dwordx4 v162, s[100:101]
	s_waitcnt vmcnt(8) lgkmcnt(0)
	s_barrier
	v_mfma_f32_16x16x32_bf16 v[64:67], v[132:135], v[176:179], v[64:67]
	v_mfma_f32_16x16x32_bf16 v[60:63], v[140:143], v[176:179], v[60:63]
	v_mfma_f32_16x16x32_bf16 v[48:51], v[132:135], v[192:195], v[48:51]
	v_mfma_f32_16x16x32_bf16 v[44:47], v[140:143], v[192:195], v[44:47]
	v_mfma_f32_16x16x32_bf16 v[30:33], v[132:135], v[232:235], v[30:33]
	v_mfma_f32_16x16x32_bf16 v[26:29], v[140:143], v[232:235], v[26:29]
	v_mfma_f32_16x16x32_bf16 v[14:17], v[132:135], v[240:243], v[14:17]
	v_mfma_f32_16x16x32_bf16 v[10:13], v[140:143], v[240:243], v[10:13]
	v_mfma_f32_16x16x32_bf16 v[64:67], v[136:139], v[180:183], v[64:67]
	v_mfma_f32_16x16x32_bf16 v[60:63], v[144:147], v[180:183], v[60:63]
	v_mfma_f32_16x16x32_bf16 v[48:51], v[136:139], v[210:213], v[48:51]
	v_mfma_f32_16x16x32_bf16 v[44:47], v[144:147], v[210:213], v[44:47]
	v_mfma_f32_16x16x32_bf16 v[30:33], v[136:139], v[236:239], v[30:33]
	v_mfma_f32_16x16x32_bf16 v[26:29], v[144:147], v[236:239], v[26:29]
	v_mfma_f32_16x16x32_bf16 v[14:17], v[136:139], v[244:247], v[14:17]
	v_mfma_f32_16x16x32_bf16 v[10:13], v[144:147], v[244:247], v[10:13]
	v_mfma_f32_16x16x32_bf16 v[56:59], v[148:151], v[176:179], v[56:59]
	v_mfma_f32_16x16x32_bf16 v[52:55], v[168:171], v[176:179], v[52:55]
	v_mfma_f32_16x16x32_bf16 v[40:43], v[148:151], v[192:195], v[40:43]
	v_mfma_f32_16x16x32_bf16 v[36:39], v[168:171], v[192:195], v[36:39]
	v_mfma_f32_16x16x32_bf16 v[22:25], v[148:151], v[232:235], v[22:25]
	v_mfma_f32_16x16x32_bf16 v[18:21], v[168:171], v[232:235], v[18:21]
	v_mfma_f32_16x16x32_bf16 v[6:9], v[148:151], v[240:243], v[6:9]
	v_mfma_f32_16x16x32_bf16 v[2:5], v[168:171], v[240:243], v[2:5]
	v_mfma_f32_16x16x32_bf16 v[56:59], v[152:155], v[180:183], v[56:59]
	v_mfma_f32_16x16x32_bf16 v[52:55], v[172:175], v[180:183], v[52:55]
	v_mfma_f32_16x16x32_bf16 v[40:43], v[152:155], v[210:213], v[40:43]
	v_mfma_f32_16x16x32_bf16 v[36:39], v[172:175], v[210:213], v[36:39]
	v_mfma_f32_16x16x32_bf16 v[22:25], v[152:155], v[236:239], v[22:25]
	v_mfma_f32_16x16x32_bf16 v[18:21], v[172:175], v[236:239], v[18:21]
	v_mfma_f32_16x16x32_bf16 v[6:9], v[152:155], v[244:247], v[6:9]
	v_mfma_f32_16x16x32_bf16 v[2:5], v[172:175], v[244:247], v[2:5]
	s_barrier
	s_add_i32 s60, s60, 2
	s_add_u32 s58, s58, 0x10000
	s_addc_u32 s59, s59, 0
	s_cmpk_gt_u32 s60, 0xa9
	s_mov_b64 s[22:23], s[42:43]
	s_cbranch_scc0 .LBB0_1261
	s_and_b64 vcc, exec, s[46:47]
	s_cbranch_vccz .LBB0_1264
	s_barrier
